# non-temporal policy on the gather's streaming x / h8 accesses (keeps the L2 for the table slice), on top of the per-slice workgroup barrier
# baseline (speedup 1.0000x reference)
;     DEVI int* eidx() const { return (int*)(ws + WS_EIDX); }
; #define LAS __attribute__((address_space(3)))
;     const int n16 = lane & 15, kq = lane >> 4;
;     LAS u32x2_t* pl = (LAS u32x2_t*)wl;
;     if (PART != 2) {
;     int e[NTL]; float g[NTL], s_u[NTL], s_v[NTL];
; #pragma unroll
;     for (int t = 0; t < NTL; ++t) { e[t] = eidx[(size_t)r * 128 + (tbase + t) * 16 + n16]; g[t] = gwv[(size_t)r * 128 + (tbase + t) * 16 + n16]; }
; #pragma unroll
;     for (int t = 0; t < NTL; ++t) { s_u[t] = su[e[t]]; s_v[t] = sv[e[t]]; }
;     const unsigned char* up[NTL];
; #pragma unroll
;     for (int t = 0; t < NTL; ++t) up[t] = u8 + (size_t)e[t] * D + kq * 16;
;     const unsigned char* hp = h8 + (n16 < 8 ? (size_t)0 : (size_t)M * D) + (size_t)r * D + kq * 16;
;     f32x4_t acc[NTL];
; #pragma unroll
;     for (int t = 0; t < NTL; ++t) acc[t] = (f32x4_t){0.f, 0.f, 0.f, 0.f};
;     u32x4_t b0[NTL], b1[NTL];
; #pragma unroll
;     for (int t = 0; t < NTL; ++t) { b0[t] = *(const u32x4_t*)(up[t]); b1[t] = *(const u32x4_t*)(up[t] + 64); }
.LBB0_1084:
	s_or_b64 exec, exec, s[40:41]
	v_readlane_b32 s2, v253, 41
	s_mov_b64 s[6:7], s[74:75]
	s_mov_b64 s[4:5], s[72:73]
	s_mov_b32 s8, s2
	v_mov_b32_e32 v1, v210
	v_readlane_b32 s48, v252, 3
	s_mov_b32 s36, s68
	s_waitcnt lgkmcnt(0)
	s_barrier
	s_cmpk_gt_i32 s48, 0x3fff
	v_and_b32_e32 v116, 15, v1
	v_and_b32_e32 v102, -16, v1
	v_lshlrev_b32_e32 v100, 4, v1
	v_cmp_gt_u32_e64 s[2:3], 16, v1
	s_mul_hi_i32 s46, s8, 0x6c000
	s_mul_i32 s47, s8, 0x6c000
	v_ashrrev_i32_e32 v103, 31, v102
	v_cmp_gt_u32_e32 vcc, 8, v116
	v_lshl_add_u32 v117, v1, 3, s85
	v_ashrrev_i32_e32 v101, 31, v100
	s_cbranch_scc1 .LBB0_1124
	s_lshl_b32 s20, s34, 9
	s_lshl_b32 s21, s34, 10
	s_lshl_b32 s11, s8, 24
	s_add_u32 s56, s6, 0x1fa42100
	s_addc_u32 s57, s7, 0
	s_add_u32 s56, s56, s11
	s_addc_u32 s57, s57, 0
	s_mov_b32 s12, s56
	s_mov_b32 s13, s57
	s_lshl_b32 s11, s48, 9
	s_add_u32 s58, s6, 0x1b292100
	s_addc_u32 s59, s7, 0
	s_add_u32 s58, s58, s11
	s_addc_u32 s59, s59, 0
	s_lshl_b32 s11, s48, 10
	s_add_u32 s60, s6, 0x2fac2100
	s_addc_u32 s61, s7, 0
	s_add_u32 s60, s60, s11
	s_addc_u32 s61, s61, 0
	s_mov_b32 s24, 0x01010101
	s_mov_b32 s25, 0x01010101
	s_mov_b32 s26, 0x02020202
	s_mov_b32 s27, 0x02020202
	s_mov_b32 s28, 0x04040404
	s_mov_b32 s29, 0x04040404
	s_mov_b32 s30, 0x08080808
	s_mov_b32 s31, 0x08080808
	s_mov_b32 s40, 0x10101010
	s_mov_b32 s41, 0x10101010
	s_mov_b32 s42, 0x20202020
	s_mov_b32 s43, 0x20202020
	s_mov_b32 s44, 0x40404040
	s_mov_b32 s45, 0x40404040
	s_mov_b32 s54, 0x80808080
	s_mov_b32 s55, 0x80808080
	v_and_b32_e32 v2, 7, v1
	v_lshrrev_b32_e32 v3, 3, v1
	v_lshlrev_b32_e32 v4, 4, v2
	v_lshlrev_b32_e32 v5, 6, v3
	v_lshlrev_b32_e32 v6, 7, v3
	v_add3_u32 v6, v6, v4, s85
	v_mov_b32_e32 v8, 0x3d000000
	v_mov_b32_e32 v9, 0x3d000000
	v_mov_b32_e32 v118, 0
	v_mov_b32_e32 v119, 0
	ds_write_b32 v6, v118 offset:4
	ds_write_b32 v6, v118 offset:12
	ds_write_b32 v6, v118 offset:1028
	ds_write_b32 v6, v118 offset:1036
	ds_write_b32 v6, v118 offset:2052
	ds_write_b32 v6, v118 offset:2060
	ds_write_b32 v6, v118 offset:3076
	ds_write_b32 v6, v118 offset:3084
	ds_write_b32 v6, v118 offset:4100
	ds_write_b32 v6, v118 offset:4108
	ds_write_b32 v6, v118 offset:5124
	ds_write_b32 v6, v118 offset:5132
	ds_write_b32 v6, v118 offset:6148
	ds_write_b32 v6, v118 offset:6156
	ds_write_b32 v6, v118 offset:7172
	ds_write_b32 v6, v118 offset:7180
	global_load_dwordx4 v[84:87], v5, s[58:59] offset:0
	global_load_dwordx4 v[88:91], v5, s[58:59] offset:16
	global_load_dwordx4 v[92:95], v5, s[58:59] offset:32
	global_load_dwordx4 v[96:99], v5, s[58:59] offset:48
	s_waitcnt vmcnt(0)
	v_lshl_add_u32 v68, v84, 10, v4
	v_lshl_add_u32 v69, v85, 10, v4
	v_lshl_add_u32 v70, v86, 10, v4
	v_lshl_add_u32 v71, v87, 10, v4
	v_lshl_add_u32 v72, v88, 10, v4
	v_lshl_add_u32 v73, v89, 10, v4
	v_lshl_add_u32 v74, v90, 10, v4
	v_lshl_add_u32 v75, v91, 10, v4
	v_lshl_add_u32 v76, v92, 10, v4
	v_lshl_add_u32 v77, v93, 10, v4
	v_lshl_add_u32 v78, v94, 10, v4
	v_lshl_add_u32 v79, v95, 10, v4
	v_lshl_add_u32 v80, v96, 10, v4
	v_lshl_add_u32 v81, v97, 10, v4
	v_lshl_add_u32 v82, v98, 10, v4
	v_lshl_add_u32 v83, v99, 10, v4
	s_add_u32 s18, s60, 0x1100000
	s_addc_u32 s19, s61, 0
	global_load_dwordx4 v[180:183], v4, s[60:61] nt
	global_load_dwordx4 v[184:187], v4, s[18:19] nt
	s_add_u32 s14, s58, s20
	s_addc_u32 s15, s59, 0
	global_load_dwordx4 v[84:87], v5, s[14:15] offset:0
	global_load_dwordx4 v[88:91], v5, s[14:15] offset:16
	global_load_dwordx4 v[92:95], v5, s[14:15] offset:32
	global_load_dwordx4 v[96:99], v5, s[14:15] offset:48
	global_load_dwordx4 v[120:123], v68, s[12:13]
	global_load_dwordx4 v[124:127], v69, s[12:13]
	global_load_dwordx4 v[128:131], v70, s[12:13]
	global_load_dwordx4 v[132:135], v71, s[12:13]
	global_load_dwordx4 v[136:139], v72, s[12:13]
	global_load_dwordx4 v[140:143], v73, s[12:13]
	global_load_dwordx4 v[144:147], v74, s[12:13]
	global_load_dwordx4 v[148:151], v75, s[12:13]
	global_load_dwordx4 v[152:155], v76, s[12:13]
	global_load_dwordx4 v[156:159], v77, s[12:13]
	global_load_dwordx4 v[160:163], v78, s[12:13]
	global_load_dwordx4 v[164:167], v79, s[12:13]
	global_load_dwordx4 v[168:171], v80, s[12:13]
	global_load_dwordx4 v[172:175], v81, s[12:13]
	global_load_dwordx4 v[188:191], v82, s[12:13]
	global_load_dwordx4 v[192:195], v83, s[12:13]
	s_mov_b32 s22, 0

;     ...
;     for (int m = 0; m < 16; m += 2) {
;         const u32x4_t a0 = *(const u32x4_t*)(hp + m * 64), a1 = *(const u32x4_t*)(hp + m * 64 + 64);
; #pragma unroll
;         for (int t = 0; t < NTL; ++t) FP8MM(a0, b0[t], acc[t]);
;         if (m + 2 < 16) {
; #pragma unroll
;             for (int t = 0; t < NTL; ++t) b0[t] = *(const u32x4_t*)(up[t] + (m + 2) * 64);
;         }
; #pragma unroll
;         for (int t = 0; t < NTL; ++t) FP8MM(a1, b1[t], acc[t]);
;         if (m + 3 < 16) {
; #pragma unroll
;             for (int t = 0; t < NTL; ++t) b1[t] = *(const u32x4_t*)(up[t] + (m + 3) * 64);
;         }
;     }
.Lg1_nobar:
	s_waitcnt vmcnt(16)
	v_cvt_pk_f32_fp8_e32 v[10:11], v180
	v_cvt_pk_f32_fp8_sdwa v[12:13], v180 src0_sel:WORD_1
	v_cvt_pk_f32_fp8_e32 v[14:15], v181
	v_cvt_pk_f32_fp8_sdwa v[16:17], v181 src0_sel:WORD_1
	v_cvt_pk_f32_fp8_e32 v[18:19], v182
	v_cvt_pk_f32_fp8_sdwa v[20:21], v182 src0_sel:WORD_1
	v_cvt_pk_f32_fp8_e32 v[22:23], v183
	v_cvt_pk_f32_fp8_sdwa v[24:25], v183 src0_sel:WORD_1
	v_cvt_pk_f32_fp8_e32 v[26:27], v184
	v_cvt_pk_f32_fp8_sdwa v[28:29], v184 src0_sel:WORD_1
	v_cvt_pk_f32_fp8_e32 v[30:31], v185
	v_cvt_pk_f32_fp8_sdwa v[32:33], v185 src0_sel:WORD_1
	v_cvt_pk_f32_fp8_e32 v[34:35], v186
	v_cvt_pk_f32_fp8_sdwa v[36:37], v186 src0_sel:WORD_1
	v_cvt_pk_f32_fp8_e32 v[38:39], v187
	v_cvt_pk_f32_fp8_sdwa v[40:41], v187 src0_sel:WORD_1
	v_pk_fma_f32 v[10:11], v[26:27], v[8:9], v[10:11]
	v_pk_fma_f32 v[12:13], v[28:29], v[8:9], v[12:13]
	v_pk_fma_f32 v[14:15], v[30:31], v[8:9], v[14:15]
	v_pk_fma_f32 v[16:17], v[32:33], v[8:9], v[16:17]
	v_pk_fma_f32 v[18:19], v[34:35], v[8:9], v[18:19]
	v_pk_fma_f32 v[20:21], v[36:37], v[8:9], v[20:21]
	v_pk_fma_f32 v[22:23], v[38:39], v[8:9], v[22:23]
	v_pk_fma_f32 v[24:25], v[40:41], v[8:9], v[24:25]
	v_lshl_add_u32 v68, v84, 10, v4
	v_lshl_add_u32 v69, v85, 10, v4
	v_lshl_add_u32 v70, v86, 10, v4
	v_lshl_add_u32 v71, v87, 10, v4
	v_lshl_add_u32 v72, v88, 10, v4
	v_lshl_add_u32 v73, v89, 10, v4
	v_lshl_add_u32 v74, v90, 10, v4
	v_lshl_add_u32 v75, v91, 10, v4
	v_lshl_add_u32 v76, v92, 10, v4
	v_lshl_add_u32 v77, v93, 10, v4
	v_lshl_add_u32 v78, v94, 10, v4
	v_lshl_add_u32 v79, v95, 10, v4
	v_lshl_add_u32 v80, v96, 10, v4
	v_lshl_add_u32 v81, v97, 10, v4
	v_lshl_add_u32 v82, v98, 10, v4
	v_lshl_add_u32 v83, v99, 10, v4
	s_add_u32 s9, s22, 1
	s_and_b32 s10, s9, 7
	s_lshr_b32 s11, s9, 3
	s_mul_i32 s23, s10, s21
	s_lshl_b32 s11, s11, 7
	s_add_u32 s16, s60, s23
	s_addc_u32 s17, s61, 0
	s_add_u32 s16, s16, s11
	s_addc_u32 s17, s17, 0
	s_add_u32 s18, s16, 0x1100000
	s_addc_u32 s19, s17, 0
	s_add_u32 s12, s56, s11
	s_addc_u32 s13, s57, 0
	s_add_u32 s9, s22, 2
	s_and_b32 s9, s9, 7
	s_mul_i32 s9, s9, s20
	s_add_u32 s14, s58, s9
	s_addc_u32 s15, s59, 0
	global_load_dwordx4 v[180:183], v4, s[16:17] nt
	global_load_dwordx4 v[184:187], v4, s[18:19] nt
	global_load_dwordx4 v[84:87], v5, s[14:15] offset:0
	global_load_dwordx4 v[88:91], v5, s[14:15] offset:16
	global_load_dwordx4 v[92:95], v5, s[14:15] offset:32
	global_load_dwordx4 v[96:99], v5, s[14:15] offset:48
	s_waitcnt vmcnt(20)
	v_cvt_pk_f32_fp8_e32 v[26:27], v120
	v_cvt_pk_f32_fp8_sdwa v[28:29], v120 src0_sel:WORD_1
	v_cvt_pk_f32_fp8_e32 v[30:31], v121
	v_cvt_pk_f32_fp8_sdwa v[32:33], v121 src0_sel:WORD_1
	v_cvt_pk_f32_fp8_e32 v[34:35], v122
	v_cvt_pk_f32_fp8_sdwa v[36:37], v122 src0_sel:WORD_1
	v_cvt_pk_f32_fp8_e32 v[38:39], v123
	v_cvt_pk_f32_fp8_sdwa v[40:41], v123 src0_sel:WORD_1
	v_cvt_pk_f32_fp8_e32 v[42:43], v124
	v_cvt_pk_f32_fp8_sdwa v[44:45], v124 src0_sel:WORD_1
	v_cvt_pk_f32_fp8_e32 v[46:47], v125
	v_cvt_pk_f32_fp8_sdwa v[48:49], v125 src0_sel:WORD_1
	v_cvt_pk_f32_fp8_e32 v[50:51], v126
	v_cvt_pk_f32_fp8_sdwa v[52:53], v126 src0_sel:WORD_1
	v_cvt_pk_f32_fp8_e32 v[54:55], v127
	v_cvt_pk_f32_fp8_sdwa v[56:57], v127 src0_sel:WORD_1
	global_load_dwordx4 v[120:123], v68, s[12:13]
	global_load_dwordx4 v[124:127], v69, s[12:13]
	v_pk_mul_f32 v[58:59], v[26:27], v[10:11]
	v_pk_mul_f32 v[60:61], v[42:43], v[10:11]
	v_pk_fma_f32 v[58:59], v[28:29], v[12:13], v[58:59]
	v_pk_fma_f32 v[60:61], v[44:45], v[12:13], v[60:61]
	v_pk_fma_f32 v[58:59], v[30:31], v[14:15], v[58:59]
	v_pk_fma_f32 v[60:61], v[46:47], v[14:15], v[60:61]
	v_pk_fma_f32 v[58:59], v[32:33], v[16:17], v[58:59]
	v_pk_fma_f32 v[60:61], v[48:49], v[16:17], v[60:61]
	v_pk_fma_f32 v[58:59], v[34:35], v[18:19], v[58:59]
	v_pk_fma_f32 v[60:61], v[50:51], v[18:19], v[60:61]
	v_pk_fma_f32 v[58:59], v[36:37], v[20:21], v[58:59]
	v_pk_fma_f32 v[60:61], v[52:53], v[20:21], v[60:61]
	v_pk_fma_f32 v[58:59], v[38:39], v[22:23], v[58:59]
	v_pk_fma_f32 v[60:61], v[54:55], v[22:23], v[60:61]
	v_pk_fma_f32 v[58:59], v[40:41], v[24:25], v[58:59]
	v_pk_fma_f32 v[60:61], v[56:57], v[24:25], v[60:61]
	v_add_f32_e32 v104, v58, v59
	v_add_f32_e32 v105, v60, v61
	s_waitcnt vmcnt(20)
	v_cvt_pk_f32_fp8_e32 v[26:27], v128
	v_cvt_pk_f32_fp8_sdwa v[28:29], v128 src0_sel:WORD_1
	v_cvt_pk_f32_fp8_e32 v[30:31], v129
	v_cvt_pk_f32_fp8_sdwa v[32:33], v129 src0_sel:WORD_1
	v_cvt_pk_f32_fp8_e32 v[34:35], v130
	v_cvt_pk_f32_fp8_sdwa v[36:37], v130 src0_sel:WORD_1
	v_cvt_pk_f32_fp8_e32 v[38:39], v131
	v_cvt_pk_f32_fp8_sdwa v[40:41], v131 src0_sel:WORD_1
	v_cvt_pk_f32_fp8_e32 v[42:43], v132
	v_cvt_pk_f32_fp8_sdwa v[44:45], v132 src0_sel:WORD_1
	v_cvt_pk_f32_fp8_e32 v[46:47], v133
	v_cvt_pk_f32_fp8_sdwa v[48:49], v133 src0_sel:WORD_1
	v_cvt_pk_f32_fp8_e32 v[50:51], v134
	v_cvt_pk_f32_fp8_sdwa v[52:53], v134 src0_sel:WORD_1
	v_cvt_pk_f32_fp8_e32 v[54:55], v135
	v_cvt_pk_f32_fp8_sdwa v[56:57], v135 src0_sel:WORD_1
	global_load_dwordx4 v[128:131], v70, s[12:13]
	global_load_dwordx4 v[132:135], v71, s[12:13]
	v_pk_mul_f32 v[58:59], v[26:27], v[10:11]
	v_pk_mul_f32 v[60:61], v[42:43], v[10:11]
	v_pk_fma_f32 v[58:59], v[28:29], v[12:13], v[58:59]
	v_pk_fma_f32 v[60:61], v[44:45], v[12:13], v[60:61]
	v_pk_fma_f32 v[58:59], v[30:31], v[14:15], v[58:59]
	v_pk_fma_f32 v[60:61], v[46:47], v[14:15], v[60:61]
	v_pk_fma_f32 v[58:59], v[32:33], v[16:17], v[58:59]
	v_pk_fma_f32 v[60:61], v[48:49], v[16:17], v[60:61]
	v_pk_fma_f32 v[58:59], v[34:35], v[18:19], v[58:59]
	v_pk_fma_f32 v[60:61], v[50:51], v[18:19], v[60:61]
	v_pk_fma_f32 v[58:59], v[36:37], v[20:21], v[58:59]
	v_pk_fma_f32 v[60:61], v[52:53], v[20:21], v[60:61]
	v_pk_fma_f32 v[58:59], v[38:39], v[22:23], v[58:59]
	v_pk_fma_f32 v[60:61], v[54:55], v[22:23], v[60:61]
	v_pk_fma_f32 v[58:59], v[40:41], v[24:25], v[58:59]
	v_pk_fma_f32 v[60:61], v[56:57], v[24:25], v[60:61]
	v_add_f32_e32 v106, v58, v59
	v_add_f32_e32 v107, v60, v61
	s_waitcnt vmcnt(20)
;     ...
;     for (int m = 0; m < 16; m += 2) {
;         const u32x4_t a0 = *(const u32x4_t*)(hp + m * 64), a1 = *(const u32x4_t*)(hp + m * 64 + 64);
; #pragma unroll
;         for (int t = 0; t < NTL; ++t) FP8MM(a0, b0[t], acc[t]);
;         if (m + 2 < 16) {
; #pragma unroll
;             for (int t = 0; t < NTL; ++t) b0[t] = *(const u32x4_t*)(up[t] + (m + 2) * 64);
;         }
; #pragma unroll
;         for (int t = 0; t < NTL; ++t) FP8MM(a1, b1[t], acc[t]);
;         if (m + 3 < 16) {
; #pragma unroll
;             for (int t = 0; t < NTL; ++t) b1[t] = *(const u32x4_t*)(up[t] + (m + 3) * 64);
;         }
;     }
	v_cvt_pk_f32_fp8_e32 v[26:27], v136
	v_cvt_pk_f32_fp8_sdwa v[28:29], v136 src0_sel:WORD_1
	v_cvt_pk_f32_fp8_e32 v[30:31], v137
	v_cvt_pk_f32_fp8_sdwa v[32:33], v137 src0_sel:WORD_1
	v_cvt_pk_f32_fp8_e32 v[34:35], v138
	v_cvt_pk_f32_fp8_sdwa v[36:37], v138 src0_sel:WORD_1
	v_cvt_pk_f32_fp8_e32 v[38:39], v139
	v_cvt_pk_f32_fp8_sdwa v[40:41], v139 src0_sel:WORD_1
	v_cvt_pk_f32_fp8_e32 v[42:43], v140
	v_cvt_pk_f32_fp8_sdwa v[44:45], v140 src0_sel:WORD_1
	v_cvt_pk_f32_fp8_e32 v[46:47], v141
	v_cvt_pk_f32_fp8_sdwa v[48:49], v141 src0_sel:WORD_1
	v_cvt_pk_f32_fp8_e32 v[50:51], v142
	v_cvt_pk_f32_fp8_sdwa v[52:53], v142 src0_sel:WORD_1
	v_cvt_pk_f32_fp8_e32 v[54:55], v143
	v_cvt_pk_f32_fp8_sdwa v[56:57], v143 src0_sel:WORD_1
	global_load_dwordx4 v[136:139], v72, s[12:13]
	global_load_dwordx4 v[140:143], v73, s[12:13]
	v_pk_mul_f32 v[58:59], v[26:27], v[10:11]
	v_pk_mul_f32 v[60:61], v[42:43], v[10:11]
	v_pk_fma_f32 v[58:59], v[28:29], v[12:13], v[58:59]
	v_pk_fma_f32 v[60:61], v[44:45], v[12:13], v[60:61]
	v_pk_fma_f32 v[58:59], v[30:31], v[14:15], v[58:59]
	v_pk_fma_f32 v[60:61], v[46:47], v[14:15], v[60:61]
	v_pk_fma_f32 v[58:59], v[32:33], v[16:17], v[58:59]
	v_pk_fma_f32 v[60:61], v[48:49], v[16:17], v[60:61]
	v_pk_fma_f32 v[58:59], v[34:35], v[18:19], v[58:59]
	v_pk_fma_f32 v[60:61], v[50:51], v[18:19], v[60:61]
	v_pk_fma_f32 v[58:59], v[36:37], v[20:21], v[58:59]
	v_pk_fma_f32 v[60:61], v[52:53], v[20:21], v[60:61]
	v_pk_fma_f32 v[58:59], v[38:39], v[22:23], v[58:59]
	v_pk_fma_f32 v[60:61], v[54:55], v[22:23], v[60:61]
	v_pk_fma_f32 v[58:59], v[40:41], v[24:25], v[58:59]
	v_pk_fma_f32 v[60:61], v[56:57], v[24:25], v[60:61]
	v_add_f32_e32 v108, v58, v59
	v_add_f32_e32 v109, v60, v61
	s_waitcnt vmcnt(20)
	v_cvt_pk_f32_fp8_e32 v[26:27], v144
	v_cvt_pk_f32_fp8_sdwa v[28:29], v144 src0_sel:WORD_1
	v_cvt_pk_f32_fp8_e32 v[30:31], v145
	v_cvt_pk_f32_fp8_sdwa v[32:33], v145 src0_sel:WORD_1
	v_cvt_pk_f32_fp8_e32 v[34:35], v146
	v_cvt_pk_f32_fp8_sdwa v[36:37], v146 src0_sel:WORD_1
	v_cvt_pk_f32_fp8_e32 v[38:39], v147
	v_cvt_pk_f32_fp8_sdwa v[40:41], v147 src0_sel:WORD_1
	v_cvt_pk_f32_fp8_e32 v[42:43], v148
	v_cvt_pk_f32_fp8_sdwa v[44:45], v148 src0_sel:WORD_1
	v_cvt_pk_f32_fp8_e32 v[46:47], v149
	v_cvt_pk_f32_fp8_sdwa v[48:49], v149 src0_sel:WORD_1
	v_cvt_pk_f32_fp8_e32 v[50:51], v150
	v_cvt_pk_f32_fp8_sdwa v[52:53], v150 src0_sel:WORD_1
	v_cvt_pk_f32_fp8_e32 v[54:55], v151
	v_cvt_pk_f32_fp8_sdwa v[56:57], v151 src0_sel:WORD_1
	global_load_dwordx4 v[144:147], v74, s[12:13]
	global_load_dwordx4 v[148:151], v75, s[12:13]
	v_pk_mul_f32 v[58:59], v[26:27], v[10:11]
	v_pk_mul_f32 v[60:61], v[42:43], v[10:11]
	v_pk_fma_f32 v[58:59], v[28:29], v[12:13], v[58:59]
	v_pk_fma_f32 v[60:61], v[44:45], v[12:13], v[60:61]
	v_pk_fma_f32 v[58:59], v[30:31], v[14:15], v[58:59]
	v_pk_fma_f32 v[60:61], v[46:47], v[14:15], v[60:61]
	v_pk_fma_f32 v[58:59], v[32:33], v[16:17], v[58:59]
	v_pk_fma_f32 v[60:61], v[48:49], v[16:17], v[60:61]
	v_pk_fma_f32 v[58:59], v[34:35], v[18:19], v[58:59]
	v_pk_fma_f32 v[60:61], v[50:51], v[18:19], v[60:61]
	v_pk_fma_f32 v[58:59], v[36:37], v[20:21], v[58:59]
	v_pk_fma_f32 v[60:61], v[52:53], v[20:21], v[60:61]
	v_pk_fma_f32 v[58:59], v[38:39], v[22:23], v[58:59]
	v_pk_fma_f32 v[60:61], v[54:55], v[22:23], v[60:61]
	v_pk_fma_f32 v[58:59], v[40:41], v[24:25], v[58:59]
	v_pk_fma_f32 v[60:61], v[56:57], v[24:25], v[60:61]
	v_add_f32_e32 v110, v58, v59
	v_add_f32_e32 v111, v60, v61
	s_waitcnt vmcnt(20)
	v_cvt_pk_f32_fp8_e32 v[26:27], v152
	v_cvt_pk_f32_fp8_sdwa v[28:29], v152 src0_sel:WORD_1
	v_cvt_pk_f32_fp8_e32 v[30:31], v153
	v_cvt_pk_f32_fp8_sdwa v[32:33], v153 src0_sel:WORD_1
	v_cvt_pk_f32_fp8_e32 v[34:35], v154
	v_cvt_pk_f32_fp8_sdwa v[36:37], v154 src0_sel:WORD_1
	v_cvt_pk_f32_fp8_e32 v[38:39], v155
	v_cvt_pk_f32_fp8_sdwa v[40:41], v155 src0_sel:WORD_1
	v_cvt_pk_f32_fp8_e32 v[42:43], v156
	v_cvt_pk_f32_fp8_sdwa v[44:45], v156 src0_sel:WORD_1
	v_cvt_pk_f32_fp8_e32 v[46:47], v157
	v_cvt_pk_f32_fp8_sdwa v[48:49], v157 src0_sel:WORD_1
	v_cvt_pk_f32_fp8_e32 v[50:51], v158
	v_cvt_pk_f32_fp8_sdwa v[52:53], v158 src0_sel:WORD_1
	v_cvt_pk_f32_fp8_e32 v[54:55], v159
	v_cvt_pk_f32_fp8_sdwa v[56:57], v159 src0_sel:WORD_1
	global_load_dwordx4 v[152:155], v76, s[12:13]
	global_load_dwordx4 v[156:159], v77, s[12:13]
	v_pk_mul_f32 v[58:59], v[26:27], v[10:11]
	v_pk_mul_f32 v[60:61], v[42:43], v[10:11]
	v_pk_fma_f32 v[58:59], v[28:29], v[12:13], v[58:59]
	v_pk_fma_f32 v[60:61], v[44:45], v[12:13], v[60:61]
	v_pk_fma_f32 v[58:59], v[30:31], v[14:15], v[58:59]
	v_pk_fma_f32 v[60:61], v[46:47], v[14:15], v[60:61]
	v_pk_fma_f32 v[58:59], v[32:33], v[16:17], v[58:59]
	v_pk_fma_f32 v[60:61], v[48:49], v[16:17], v[60:61]
	v_pk_fma_f32 v[58:59], v[34:35], v[18:19], v[58:59]
	v_pk_fma_f32 v[60:61], v[50:51], v[18:19], v[60:61]
	v_pk_fma_f32 v[58:59], v[36:37], v[20:21], v[58:59]
	v_pk_fma_f32 v[60:61], v[52:53], v[20:21], v[60:61]
	v_pk_fma_f32 v[58:59], v[38:39], v[22:23], v[58:59]
	v_pk_fma_f32 v[60:61], v[54:55], v[22:23], v[60:61]
	v_pk_fma_f32 v[58:59], v[40:41], v[24:25], v[58:59]
	v_pk_fma_f32 v[60:61], v[56:57], v[24:25], v[60:61]
	v_add_f32_e32 v112, v58, v59
	v_add_f32_e32 v113, v60, v61
	s_waitcnt vmcnt(20)
;     ...
;     for (int m = 0; m < 16; m += 2) {
;         const u32x4_t a0 = *(const u32x4_t*)(hp + m * 64), a1 = *(const u32x4_t*)(hp + m * 64 + 64);
; #pragma unroll
;         for (int t = 0; t < NTL; ++t) FP8MM(a0, b0[t], acc[t]);
;         if (m + 2 < 16) {
; #pragma unroll
;             for (int t = 0; t < NTL; ++t) b0[t] = *(const u32x4_t*)(up[t] + (m + 2) * 64);
;         }
; #pragma unroll
;         for (int t = 0; t < NTL; ++t) FP8MM(a1, b1[t], acc[t]);
;         if (m + 3 < 16) {
; #pragma unroll
;             for (int t = 0; t < NTL; ++t) b1[t] = *(const u32x4_t*)(up[t] + (m + 3) * 64);
;         }
;     }
;     ...
; #pragma unroll
;     for (int t = 0; t < NTL; ++t) { const float lo = __shfl_xor(acc[t][0], 32); const float dot = (acc[t][0] + lo * (1.f / 32.f)) * s_u[t];
	v_cvt_pk_f32_fp8_e32 v[26:27], v160
	v_cvt_pk_f32_fp8_sdwa v[28:29], v160 src0_sel:WORD_1
	v_cvt_pk_f32_fp8_e32 v[30:31], v161
	v_cvt_pk_f32_fp8_sdwa v[32:33], v161 src0_sel:WORD_1
	v_cvt_pk_f32_fp8_e32 v[34:35], v162
	v_cvt_pk_f32_fp8_sdwa v[36:37], v162 src0_sel:WORD_1
	v_cvt_pk_f32_fp8_e32 v[38:39], v163
	v_cvt_pk_f32_fp8_sdwa v[40:41], v163 src0_sel:WORD_1
	v_cvt_pk_f32_fp8_e32 v[42:43], v164
	v_cvt_pk_f32_fp8_sdwa v[44:45], v164 src0_sel:WORD_1
	v_cvt_pk_f32_fp8_e32 v[46:47], v165
	v_cvt_pk_f32_fp8_sdwa v[48:49], v165 src0_sel:WORD_1
	v_cvt_pk_f32_fp8_e32 v[50:51], v166
	v_cvt_pk_f32_fp8_sdwa v[52:53], v166 src0_sel:WORD_1
	v_cvt_pk_f32_fp8_e32 v[54:55], v167
	v_cvt_pk_f32_fp8_sdwa v[56:57], v167 src0_sel:WORD_1
	global_load_dwordx4 v[160:163], v78, s[12:13]
	global_load_dwordx4 v[164:167], v79, s[12:13]
	v_pk_mul_f32 v[58:59], v[26:27], v[10:11]
	v_pk_mul_f32 v[60:61], v[42:43], v[10:11]
	v_pk_fma_f32 v[58:59], v[28:29], v[12:13], v[58:59]
	v_pk_fma_f32 v[60:61], v[44:45], v[12:13], v[60:61]
	v_pk_fma_f32 v[58:59], v[30:31], v[14:15], v[58:59]
	v_pk_fma_f32 v[60:61], v[46:47], v[14:15], v[60:61]
	v_pk_fma_f32 v[58:59], v[32:33], v[16:17], v[58:59]
	v_pk_fma_f32 v[60:61], v[48:49], v[16:17], v[60:61]
	v_pk_fma_f32 v[58:59], v[34:35], v[18:19], v[58:59]
	v_pk_fma_f32 v[60:61], v[50:51], v[18:19], v[60:61]
	v_pk_fma_f32 v[58:59], v[36:37], v[20:21], v[58:59]
	v_pk_fma_f32 v[60:61], v[52:53], v[20:21], v[60:61]
	v_pk_fma_f32 v[58:59], v[38:39], v[22:23], v[58:59]
	v_pk_fma_f32 v[60:61], v[54:55], v[22:23], v[60:61]
	v_pk_fma_f32 v[58:59], v[40:41], v[24:25], v[58:59]
	v_pk_fma_f32 v[60:61], v[56:57], v[24:25], v[60:61]
	v_add_f32_e32 v114, v58, v59
	v_add_f32_e32 v115, v60, v61
	s_waitcnt vmcnt(20)
	v_cvt_pk_f32_fp8_e32 v[26:27], v168
	v_cvt_pk_f32_fp8_sdwa v[28:29], v168 src0_sel:WORD_1
	v_cvt_pk_f32_fp8_e32 v[30:31], v169
	v_cvt_pk_f32_fp8_sdwa v[32:33], v169 src0_sel:WORD_1
	v_cvt_pk_f32_fp8_e32 v[34:35], v170
	v_cvt_pk_f32_fp8_sdwa v[36:37], v170 src0_sel:WORD_1
	v_cvt_pk_f32_fp8_e32 v[38:39], v171
	v_cvt_pk_f32_fp8_sdwa v[40:41], v171 src0_sel:WORD_1
	v_cvt_pk_f32_fp8_e32 v[42:43], v172
	v_cvt_pk_f32_fp8_sdwa v[44:45], v172 src0_sel:WORD_1
	v_cvt_pk_f32_fp8_e32 v[46:47], v173
	v_cvt_pk_f32_fp8_sdwa v[48:49], v173 src0_sel:WORD_1
	v_cvt_pk_f32_fp8_e32 v[50:51], v174
	v_cvt_pk_f32_fp8_sdwa v[52:53], v174 src0_sel:WORD_1
	v_cvt_pk_f32_fp8_e32 v[54:55], v175
	v_cvt_pk_f32_fp8_sdwa v[56:57], v175 src0_sel:WORD_1
	global_load_dwordx4 v[168:171], v80, s[12:13]
	global_load_dwordx4 v[172:175], v81, s[12:13]
	v_pk_mul_f32 v[58:59], v[26:27], v[10:11]
	v_pk_mul_f32 v[60:61], v[42:43], v[10:11]
	v_pk_fma_f32 v[58:59], v[28:29], v[12:13], v[58:59]
	v_pk_fma_f32 v[60:61], v[44:45], v[12:13], v[60:61]
	v_pk_fma_f32 v[58:59], v[30:31], v[14:15], v[58:59]
	v_pk_fma_f32 v[60:61], v[46:47], v[14:15], v[60:61]
	v_pk_fma_f32 v[58:59], v[32:33], v[16:17], v[58:59]
	v_pk_fma_f32 v[60:61], v[48:49], v[16:17], v[60:61]
	v_pk_fma_f32 v[58:59], v[34:35], v[18:19], v[58:59]
	v_pk_fma_f32 v[60:61], v[50:51], v[18:19], v[60:61]
	v_pk_fma_f32 v[58:59], v[36:37], v[20:21], v[58:59]
	v_pk_fma_f32 v[60:61], v[52:53], v[20:21], v[60:61]
	v_pk_fma_f32 v[58:59], v[38:39], v[22:23], v[58:59]
	v_pk_fma_f32 v[60:61], v[54:55], v[22:23], v[60:61]
	v_pk_fma_f32 v[58:59], v[40:41], v[24:25], v[58:59]
	v_pk_fma_f32 v[60:61], v[56:57], v[24:25], v[60:61]
	v_add_f32_e32 v62, v58, v59
	v_add_f32_e32 v63, v60, v61
	s_waitcnt vmcnt(20)
	v_cvt_pk_f32_fp8_e32 v[26:27], v188
	v_cvt_pk_f32_fp8_sdwa v[28:29], v188 src0_sel:WORD_1
	v_cvt_pk_f32_fp8_e32 v[30:31], v189
	v_cvt_pk_f32_fp8_sdwa v[32:33], v189 src0_sel:WORD_1
	v_cvt_pk_f32_fp8_e32 v[34:35], v190
	v_cvt_pk_f32_fp8_sdwa v[36:37], v190 src0_sel:WORD_1
	v_cvt_pk_f32_fp8_e32 v[38:39], v191
	v_cvt_pk_f32_fp8_sdwa v[40:41], v191 src0_sel:WORD_1
	v_cvt_pk_f32_fp8_e32 v[42:43], v192
	v_cvt_pk_f32_fp8_sdwa v[44:45], v192 src0_sel:WORD_1
	v_cvt_pk_f32_fp8_e32 v[46:47], v193
	v_cvt_pk_f32_fp8_sdwa v[48:49], v193 src0_sel:WORD_1
	v_cvt_pk_f32_fp8_e32 v[50:51], v194
	v_cvt_pk_f32_fp8_sdwa v[52:53], v194 src0_sel:WORD_1
	v_cvt_pk_f32_fp8_e32 v[54:55], v195
	v_cvt_pk_f32_fp8_sdwa v[56:57], v195 src0_sel:WORD_1
	global_load_dwordx4 v[188:191], v82, s[12:13]
	global_load_dwordx4 v[192:195], v83, s[12:13]
	v_pk_mul_f32 v[58:59], v[26:27], v[10:11]
	v_pk_mul_f32 v[60:61], v[42:43], v[10:11]
	v_pk_fma_f32 v[58:59], v[28:29], v[12:13], v[58:59]
	v_pk_fma_f32 v[60:61], v[44:45], v[12:13], v[60:61]
	v_pk_fma_f32 v[58:59], v[30:31], v[14:15], v[58:59]
	v_pk_fma_f32 v[60:61], v[46:47], v[14:15], v[60:61]
	v_pk_fma_f32 v[58:59], v[32:33], v[16:17], v[58:59]
	v_pk_fma_f32 v[60:61], v[48:49], v[16:17], v[60:61]
	v_pk_fma_f32 v[58:59], v[34:35], v[18:19], v[58:59]
	v_pk_fma_f32 v[60:61], v[50:51], v[18:19], v[60:61]
	v_pk_fma_f32 v[58:59], v[36:37], v[20:21], v[58:59]
	v_pk_fma_f32 v[60:61], v[52:53], v[20:21], v[60:61]
	v_pk_fma_f32 v[58:59], v[38:39], v[22:23], v[58:59]
	v_pk_fma_f32 v[60:61], v[54:55], v[22:23], v[60:61]
	v_pk_fma_f32 v[58:59], v[40:41], v[24:25], v[58:59]
	v_pk_fma_f32 v[60:61], v[56:57], v[24:25], v[60:61]
	v_add_f32_e32 v64, v58, v59
	v_add_f32_e32 v65, v60, v61
	s_nop 1
	v_add_f32_dpp v104, v104, v104 quad_perm:[1,0,3,2] row_mask:0xf bank_mask:0xf
	v_add_f32_dpp v105, v105, v105 quad_perm:[1,0,3,2] row_mask:0xf bank_mask:0xf
	v_add_f32_dpp v106, v106, v106 quad_perm:[1,0,3,2] row_mask:0xf bank_mask:0xf
	v_add_f32_dpp v107, v107, v107 quad_perm:[1,0,3,2] row_mask:0xf bank_mask:0xf
	v_add_f32_dpp v108, v108, v108 quad_perm:[1,0,3,2] row_mask:0xf bank_mask:0xf
	v_add_f32_dpp v109, v109, v109 quad_perm:[1,0,3,2] row_mask:0xf bank_mask:0xf
;     DEVI int* eidx() const { return (int*)(ws + WS_EIDX); }
; DEVI float gelu_f(float x) { const float u = 0.7978845608028654f * (x + 0.044715f * x * x * x); return x * __builtin_amdgcn_rcpf(1.f + __expf(-2.f * u)); }
;     ...
;     for (int t = 0; t < NTL; ++t) { e[t] = eidx[(size_t)r * 128 + (tbase + t) * 16 + n16]; g[t] = gwv[(size_t)r * 128 + (tbase + t) * 16 + n16]; }
; #pragma unroll
;     for (int t = 0; t < NTL; ++t) { s_u[t] = su[e[t]]; s_v[t] = sv[e[t]]; }
;     const unsigned char* up[NTL];
; #pragma unroll
;     for (int t = 0; t < NTL; ++t) up[t] = u8 + (size_t)e[t] * D + kq * 16;
;     const unsigned char* hp = h8 + (n16 < 8 ? (size_t)0 : (size_t)M * D) + (size_t)r * D + kq * 16;
;     f32x4_t acc[NTL];
; #pragma unroll
;     for (int t = 0; t < NTL; ++t) acc[t] = (f32x4_t){0.f, 0.f, 0.f, 0.f};
;     u32x4_t b0[NTL], b1[NTL];
; #pragma unroll
;     for (int t = 0; t < NTL; ++t) { b0[t] = *(const u32x4_t*)(up[t]); b1[t] = *(const u32x4_t*)(up[t] + 64); }
;     ...
;     for (int m = 0; m < 16; m += 2) {
;         const u32x4_t a0 = *(const u32x4_t*)(hp + m * 64), a1 = *(const u32x4_t*)(hp + m * 64 + 64);
; #pragma unroll
;         for (int t = 0; t < NTL; ++t) FP8MM(a0, b0[t], acc[t]);
;         if (m + 2 < 16) {
; #pragma unroll
;             for (int t = 0; t < NTL; ++t) b0[t] = *(const u32x4_t*)(up[t] + (m + 2) * 64);
;         }
; #pragma unroll
;         for (int t = 0; t < NTL; ++t) FP8MM(a1, b1[t], acc[t]);
;         if (m + 3 < 16) {
; #pragma unroll
;             for (int t = 0; t < NTL; ++t) b1[t] = *(const u32x4_t*)(up[t] + (m + 3) * 64);
;         }
;     }
;     ...
; #pragma unroll
;     for (int t = 0; t < NTL; ++t) { const float lo = __shfl_xor(acc[t][0], 32); const float dot = (acc[t][0] + lo * (1.f / 32.f)) * s_u[t];
;         if (kq == 0) pl[t * 16 + n16] = (u32x2_t){(unsigned)e[t], __float_as_uint(g[t] * gelu_f(dot) * s_v[t])}; }
	v_add_f32_dpp v110, v110, v110 quad_perm:[1,0,3,2] row_mask:0xf bank_mask:0xf
	v_add_f32_dpp v111, v111, v111 quad_perm:[1,0,3,2] row_mask:0xf bank_mask:0xf
	v_add_f32_dpp v112, v112, v112 quad_perm:[1,0,3,2] row_mask:0xf bank_mask:0xf
	v_add_f32_dpp v113, v113, v113 quad_perm:[1,0,3,2] row_mask:0xf bank_mask:0xf
	v_add_f32_dpp v114, v114, v114 quad_perm:[1,0,3,2] row_mask:0xf bank_mask:0xf
	v_add_f32_dpp v115, v115, v115 quad_perm:[1,0,3,2] row_mask:0xf bank_mask:0xf
	v_add_f32_dpp v62, v62, v62 quad_perm:[1,0,3,2] row_mask:0xf bank_mask:0xf
	v_add_f32_dpp v63, v63, v63 quad_perm:[1,0,3,2] row_mask:0xf bank_mask:0xf
	v_add_f32_dpp v64, v64, v64 quad_perm:[1,0,3,2] row_mask:0xf bank_mask:0xf
	v_add_f32_dpp v65, v65, v65 quad_perm:[1,0,3,2] row_mask:0xf bank_mask:0xf
	v_add_f32_dpp v104, v104, v104 quad_perm:[2,3,0,1] row_mask:0xf bank_mask:0xf
	v_add_f32_dpp v105, v105, v105 quad_perm:[2,3,0,1] row_mask:0xf bank_mask:0xf
	v_add_f32_dpp v106, v106, v106 quad_perm:[2,3,0,1] row_mask:0xf bank_mask:0xf
	v_add_f32_dpp v107, v107, v107 quad_perm:[2,3,0,1] row_mask:0xf bank_mask:0xf
	v_add_f32_dpp v108, v108, v108 quad_perm:[2,3,0,1] row_mask:0xf bank_mask:0xf
	v_add_f32_dpp v109, v109, v109 quad_perm:[2,3,0,1] row_mask:0xf bank_mask:0xf
	v_add_f32_dpp v110, v110, v110 quad_perm:[2,3,0,1] row_mask:0xf bank_mask:0xf
	v_add_f32_dpp v111, v111, v111 quad_perm:[2,3,0,1] row_mask:0xf bank_mask:0xf
	v_add_f32_dpp v112, v112, v112 quad_perm:[2,3,0,1] row_mask:0xf bank_mask:0xf
	v_add_f32_dpp v113, v113, v113 quad_perm:[2,3,0,1] row_mask:0xf bank_mask:0xf
	v_add_f32_dpp v114, v114, v114 quad_perm:[2,3,0,1] row_mask:0xf bank_mask:0xf
	v_add_f32_dpp v115, v115, v115 quad_perm:[2,3,0,1] row_mask:0xf bank_mask:0xf
	v_add_f32_dpp v62, v62, v62 quad_perm:[2,3,0,1] row_mask:0xf bank_mask:0xf
	v_add_f32_dpp v63, v63, v63 quad_perm:[2,3,0,1] row_mask:0xf bank_mask:0xf
	v_add_f32_dpp v64, v64, v64 quad_perm:[2,3,0,1] row_mask:0xf bank_mask:0xf
	v_add_f32_dpp v65, v65, v65 quad_perm:[2,3,0,1] row_mask:0xf bank_mask:0xf
	v_add_f32_dpp v104, v104, v104 row_half_mirror row_mask:0xf bank_mask:0xf
	v_add_f32_dpp v105, v105, v105 row_half_mirror row_mask:0xf bank_mask:0xf
	v_add_f32_dpp v106, v106, v106 row_half_mirror row_mask:0xf bank_mask:0xf
	v_add_f32_dpp v107, v107, v107 row_half_mirror row_mask:0xf bank_mask:0xf
	v_add_f32_dpp v108, v108, v108 row_half_mirror row_mask:0xf bank_mask:0xf
	v_add_f32_dpp v109, v109, v109 row_half_mirror row_mask:0xf bank_mask:0xf
	v_add_f32_dpp v110, v110, v110 row_half_mirror row_mask:0xf bank_mask:0xf
	v_add_f32_dpp v111, v111, v111 row_half_mirror row_mask:0xf bank_mask:0xf
	v_add_f32_dpp v112, v112, v112 row_half_mirror row_mask:0xf bank_mask:0xf
	v_add_f32_dpp v113, v113, v113 row_half_mirror row_mask:0xf bank_mask:0xf
	v_add_f32_dpp v114, v114, v114 row_half_mirror row_mask:0xf bank_mask:0xf
	v_add_f32_dpp v115, v115, v115 row_half_mirror row_mask:0xf bank_mask:0xf
	v_add_f32_dpp v62, v62, v62 row_half_mirror row_mask:0xf bank_mask:0xf
	v_add_f32_dpp v63, v63, v63 row_half_mirror row_mask:0xf bank_mask:0xf
	v_add_f32_dpp v64, v64, v64 row_half_mirror row_mask:0xf bank_mask:0xf
	v_add_f32_dpp v65, v65, v65 row_half_mirror row_mask:0xf bank_mask:0xf
	v_cndmask_b32_e64 v118, v118, v104, s[24:25]
	v_cndmask_b32_e64 v119, v119, v105, s[24:25]
	v_cndmask_b32_e64 v118, v118, v106, s[26:27]
	v_cndmask_b32_e64 v119, v119, v107, s[26:27]
	v_cndmask_b32_e64 v118, v118, v108, s[28:29]
	v_cndmask_b32_e64 v119, v119, v109, s[28:29]
	v_cndmask_b32_e64 v118, v118, v110, s[30:31]
	v_cndmask_b32_e64 v119, v119, v111, s[30:31]
	v_cndmask_b32_e64 v118, v118, v112, s[40:41]
	v_cndmask_b32_e64 v119, v119, v113, s[40:41]
	v_cndmask_b32_e64 v118, v118, v114, s[42:43]
	v_cndmask_b32_e64 v119, v119, v115, s[42:43]
	v_cndmask_b32_e64 v118, v118, v62, s[44:45]
	v_cndmask_b32_e64 v119, v119, v63, s[44:45]
	v_cndmask_b32_e64 v118, v118, v64, s[54:55]
	v_cndmask_b32_e64 v119, v119, v65, s[54:55]
	s_and_b32 s9, s22, 7
	s_lshl_b32 s9, s9, 10
	v_add_u32_e32 v7, s9, v6
	ds_add_f32 v7, v118 offset:4
	ds_add_f32 v7, v119 offset:12
	s_add_u32 s22, s22, 1
	s_cmp_lg_u32 s22, 64
	s_cbranch_scc1 .Lg1_loop
	s_waitcnt vmcnt(0) lgkmcnt(0)
	s_lshl_b32 s9, s48, 9
	s_lshl_b32 s20, s34, 9
	s_add_u32 s10, s6, 0x1b292100
	s_addc_u32 s11, s7, 0
	s_add_u32 s10, s10, s9
	s_addc_u32 s11, s11, 0
	s_add_u32 s12, s6, 0x1bb12100
	s_addc_u32 s13, s7, 0
	s_add_u32 s12, s12, s9
	s_addc_u32 s13, s13, 0
	s_lshl_b32 s9, s8, 16
	s_add_u32 s16, s6, 0x2fa42100
	s_addc_u32 s17, s7, 0
	s_add_u32 s16, s16, s9
	s_addc_u32 s17, s17, 0
	s_add_u32 s18, s16, 0x40000
	s_addc_u32 s19, s17, 0
	v_lshlrev_b32_e32 v2, 3, v1
	v_lshl_add_u32 v3, v1, 4, s85
	ds_read_b128 v[68:71], v3 offset:0
	ds_read_b128 v[72:75], v3 offset:1024
	ds_read_b128 v[76:79], v3 offset:2048
	ds_read_b128 v[80:83], v3 offset:3072
	ds_read_b128 v[84:87], v3 offset:4096
	ds_read_b128 v[88:91], v3 offset:5120
	ds_read_b128 v[92:95], v3 offset:6144
	ds_read_b128 v[96:99], v3 offset:7168
	global_load_dwordx2 v[20:21], v2, s[10:11]
	global_load_dwordx2 v[22:23], v2, s[12:13]
	s_add_u32 s10, s10, s20
	s_addc_u32 s11, s11, 0
	s_add_u32 s12, s12, s20
	s_addc_u32 s13, s13, 0
	global_load_dwordx2 v[24:25], v2, s[10:11]
	global_load_dwordx2 v[26:27], v2, s[12:13]
	s_add_u32 s10, s10, s20
	s_addc_u32 s11, s11, 0
	s_add_u32 s12, s12, s20
	s_addc_u32 s13, s13, 0
	global_load_dwordx2 v[28:29], v2, s[10:11]
	global_load_dwordx2 v[30:31], v2, s[12:13]
	s_add_u32 s10, s10, s20
	s_addc_u32 s11, s11, 0
	s_add_u32 s12, s12, s20
	s_addc_u32 s13, s13, 0
	global_load_dwordx2 v[32:33], v2, s[10:11]
	global_load_dwordx2 v[34:35], v2, s[12:13]
	s_add_u32 s10, s10, s20
	s_addc_u32 s11, s11, 0
	s_add_u32 s12, s12, s20
	s_addc_u32 s13, s13, 0
	global_load_dwordx2 v[36:37], v2, s[10:11]
	global_load_dwordx2 v[38:39], v2, s[12:13]
	s_add_u32 s10, s10, s20
	s_addc_u32 s11, s11, 0
	s_add_u32 s12, s12, s20
	s_addc_u32 s13, s13, 0
	global_load_dwordx2 v[40:41], v2, s[10:11]
	global_load_dwordx2 v[42:43], v2, s[12:13]
	s_add_u32 s10, s10, s20
	s_addc_u32 s11, s11, 0
	s_add_u32 s12, s12, s20
	s_addc_u32 s13, s13, 0
	global_load_dwordx2 v[44:45], v2, s[10:11]
	global_load_dwordx2 v[46:47], v2, s[12:13]
	s_add_u32 s10, s10, s20
	s_addc_u32 s11, s11, 0
	s_add_u32 s12, s12, s20
	s_addc_u32 s13, s13, 0
	global_load_dwordx2 v[48:49], v2, s[10:11]
	global_load_dwordx2 v[50:51], v2, s[12:13]
	s_add_u32 s10, s10, s20
	s_addc_u32 s11, s11, 0
	s_add_u32 s12, s12, s20
	s_addc_u32 s13, s13, 0
	s_waitcnt vmcnt(15)
; DEVI float gelu_f(float x) { const float u = 0.7978845608028654f * (x + 0.044715f * x * x * x); return x * __builtin_amdgcn_rcpf(1.f + __expf(-2.f * u)); }
;     ...
;     for (int t = 0; t < NTL; ++t) { const float lo = __shfl_xor(acc[t][0], 32); const float dot = (acc[t][0] + lo * (1.f / 32.f)) * s_u[t];
;         if (kq == 0) pl[t * 16 + n16] = (u32x2_t){(unsigned)e[t], __float_as_uint(g[t] * gelu_f(dot) * s_v[t])}; }
	v_lshlrev_b32_e32 v4, 2, v20
	v_lshlrev_b32_e32 v5, 2, v21
	global_load_dword v120, v4, s[16:17]
	global_load_dword v121, v5, s[16:17]
	global_load_dword v122, v4, s[18:19]
	global_load_dword v123, v5, s[18:19]
	s_waitcnt vmcnt(17)
	v_lshlrev_b32_e32 v4, 2, v24
	v_lshlrev_b32_e32 v5, 2, v25
	global_load_dword v124, v4, s[16:17]
	global_load_dword v125, v5, s[16:17]
	global_load_dword v126, v4, s[18:19]
	global_load_dword v127, v5, s[18:19]
	s_waitcnt vmcnt(19)
	v_lshlrev_b32_e32 v4, 2, v28
	v_lshlrev_b32_e32 v5, 2, v29
	global_load_dword v128, v4, s[16:17]
	global_load_dword v129, v5, s[16:17]
	global_load_dword v130, v4, s[18:19]
	global_load_dword v131, v5, s[18:19]
	s_waitcnt vmcnt(21)
	v_lshlrev_b32_e32 v4, 2, v32
	v_lshlrev_b32_e32 v5, 2, v33
	global_load_dword v132, v4, s[16:17]
	global_load_dword v133, v5, s[16:17]
	global_load_dword v134, v4, s[18:19]
	global_load_dword v135, v5, s[18:19]
	s_waitcnt vmcnt(23)
	v_lshlrev_b32_e32 v4, 2, v36
	v_lshlrev_b32_e32 v5, 2, v37
	global_load_dword v136, v4, s[16:17]
	global_load_dword v137, v5, s[16:17]
	global_load_dword v138, v4, s[18:19]
	global_load_dword v139, v5, s[18:19]
	s_waitcnt vmcnt(25)
	v_lshlrev_b32_e32 v4, 2, v40
	v_lshlrev_b32_e32 v5, 2, v41
	global_load_dword v140, v4, s[16:17]
	global_load_dword v141, v5, s[16:17]
	global_load_dword v142, v4, s[18:19]
	global_load_dword v143, v5, s[18:19]
	s_waitcnt vmcnt(27)
	v_lshlrev_b32_e32 v4, 2, v44
	v_lshlrev_b32_e32 v5, 2, v45
	global_load_dword v144, v4, s[16:17]
	global_load_dword v145, v5, s[16:17]
	global_load_dword v146, v4, s[18:19]
	global_load_dword v147, v5, s[18:19]
	s_waitcnt vmcnt(29)
	v_lshlrev_b32_e32 v4, 2, v48
	v_lshlrev_b32_e32 v5, 2, v49
	global_load_dword v148, v4, s[16:17]
	global_load_dword v149, v5, s[16:17]
	global_load_dword v150, v4, s[18:19]
	global_load_dword v151, v5, s[18:19]
	s_waitcnt lgkmcnt(0)
	s_waitcnt vmcnt(28)
	v_mul_f32_e32 v69, v69, v120
	v_mul_f32_e32 v6, 0x3d372713, v69
	v_mul_f32_e32 v6, v69, v6
	v_fma_f32 v6, v69, v6, v69
	v_mul_f32_e32 v6, 0x3f4c422a, v6
	v_mul_f32_e32 v6, -2.0, v6
	v_mul_f32_e32 v6, 0x3fb8aa3b, v6
	v_exp_f32_e32 v6, v6
	s_nop 0
	v_add_f32_e32 v6, 1.0, v6
	v_rcp_f32_e32 v6, v6
	s_nop 0
	v_mul_f32_e32 v69, v69, v6
	v_mul_f32_e32 v69, v22, v69
	v_mul_f32_e32 v69, v122, v69
	v_mul_f32_e32 v71, v71, v121
	v_mul_f32_e32 v7, 0x3d372713, v71
	v_mul_f32_e32 v7, v71, v7
	v_fma_f32 v7, v71, v7, v71
	v_mul_f32_e32 v7, 0x3f4c422a, v7
	v_mul_f32_e32 v7, -2.0, v7
	v_mul_f32_e32 v7, 0x3fb8aa3b, v7
	v_exp_f32_e32 v7, v7
	s_nop 0
	v_add_f32_e32 v7, 1.0, v7
	v_rcp_f32_e32 v7, v7
	s_nop 0
	v_mul_f32_e32 v71, v71, v7
	v_mul_f32_e32 v71, v23, v71
	v_mul_f32_e32 v71, v123, v71
	v_mov_b32_e32 v68, v20
	v_mov_b32_e32 v70, v21
	ds_write_b128 v3, v[68:71] offset:0
	s_waitcnt vmcnt(24)
	v_mul_f32_e32 v73, v73, v124
	v_mul_f32_e32 v6, 0x3d372713, v73
	v_mul_f32_e32 v6, v73, v6
	v_fma_f32 v6, v73, v6, v73
	v_mul_f32_e32 v6, 0x3f4c422a, v6
	v_mul_f32_e32 v6, -2.0, v6
	v_mul_f32_e32 v6, 0x3fb8aa3b, v6
	v_exp_f32_e32 v6, v6
	s_nop 0
	v_add_f32_e32 v6, 1.0, v6
	v_rcp_f32_e32 v6, v6
	s_nop 0
	v_mul_f32_e32 v73, v73, v6
	v_mul_f32_e32 v73, v26, v73
	v_mul_f32_e32 v73, v126, v73
	v_mul_f32_e32 v75, v75, v125
	v_mul_f32_e32 v7, 0x3d372713, v75
	v_mul_f32_e32 v7, v75, v7
	v_fma_f32 v7, v75, v7, v75
	v_mul_f32_e32 v7, 0x3f4c422a, v7
	v_mul_f32_e32 v7, -2.0, v7
	v_mul_f32_e32 v7, 0x3fb8aa3b, v7
	v_exp_f32_e32 v7, v7
	s_nop 0
	v_add_f32_e32 v7, 1.0, v7
	v_rcp_f32_e32 v7, v7
	s_nop 0
	v_mul_f32_e32 v75, v75, v7
	v_mul_f32_e32 v75, v27, v75
	v_mul_f32_e32 v75, v127, v75
	v_mov_b32_e32 v72, v24
	v_mov_b32_e32 v74, v25
	ds_write_b128 v3, v[72:75] offset:1024
	s_waitcnt vmcnt(20)
	v_mul_f32_e32 v77, v77, v128
	v_mul_f32_e32 v6, 0x3d372713, v77
	v_mul_f32_e32 v6, v77, v6
	v_fma_f32 v6, v77, v6, v77
	v_mul_f32_e32 v6, 0x3f4c422a, v6
	v_mul_f32_e32 v6, -2.0, v6
	v_mul_f32_e32 v6, 0x3fb8aa3b, v6
	v_exp_f32_e32 v6, v6
	s_nop 0
	v_add_f32_e32 v6, 1.0, v6
	v_rcp_f32_e32 v6, v6
	s_nop 0
	v_mul_f32_e32 v77, v77, v6
	v_mul_f32_e32 v77, v30, v77
	v_mul_f32_e32 v77, v130, v77
	v_mul_f32_e32 v79, v79, v129
	v_mul_f32_e32 v7, 0x3d372713, v79
	v_mul_f32_e32 v7, v79, v7
	v_fma_f32 v7, v79, v7, v79
	v_mul_f32_e32 v7, 0x3f4c422a, v7
	v_mul_f32_e32 v7, -2.0, v7
	v_mul_f32_e32 v7, 0x3fb8aa3b, v7
	v_exp_f32_e32 v7, v7
	s_nop 0
	v_add_f32_e32 v7, 1.0, v7
	v_rcp_f32_e32 v7, v7
	s_nop 0
	v_mul_f32_e32 v79, v79, v7
	v_mul_f32_e32 v79, v31, v79
	v_mul_f32_e32 v79, v131, v79
	v_mov_b32_e32 v76, v28
	v_mov_b32_e32 v78, v29
	ds_write_b128 v3, v[76:79] offset:2048
	s_waitcnt vmcnt(16)
	v_mul_f32_e32 v81, v81, v132
	v_mul_f32_e32 v6, 0x3d372713, v81
	v_mul_f32_e32 v6, v81, v6
	v_fma_f32 v6, v81, v6, v81
	v_mul_f32_e32 v6, 0x3f4c422a, v6
	v_mul_f32_e32 v6, -2.0, v6
	v_mul_f32_e32 v6, 0x3fb8aa3b, v6
	v_exp_f32_e32 v6, v6
	s_nop 0
	v_add_f32_e32 v6, 1.0, v6
	v_rcp_f32_e32 v6, v6
	s_nop 0
	v_mul_f32_e32 v81, v81, v6
	v_mul_f32_e32 v81, v34, v81
	v_mul_f32_e32 v81, v134, v81
	v_mul_f32_e32 v83, v83, v133
	v_mul_f32_e32 v7, 0x3d372713, v83
	v_mul_f32_e32 v7, v83, v7
	v_fma_f32 v7, v83, v7, v83
	v_mul_f32_e32 v7, 0x3f4c422a, v7
	v_mul_f32_e32 v7, -2.0, v7
	v_mul_f32_e32 v7, 0x3fb8aa3b, v7
	v_exp_f32_e32 v7, v7
	s_nop 0
	v_add_f32_e32 v7, 1.0, v7
	v_rcp_f32_e32 v7, v7
	s_nop 0
	v_mul_f32_e32 v83, v83, v7
	v_mul_f32_e32 v83, v35, v83
	v_mul_f32_e32 v83, v135, v83
	v_mov_b32_e32 v80, v32
	v_mov_b32_e32 v82, v33
	ds_write_b128 v3, v[80:83] offset:3072
	s_waitcnt vmcnt(12)
; DEVI float gelu_f(float x) { const float u = 0.7978845608028654f * (x + 0.044715f * x * x * x); return x * __builtin_amdgcn_rcpf(1.f + __expf(-2.f * u)); }
;     ...
;     for (int t = 0; t < NTL; ++t) { const float lo = __shfl_xor(acc[t][0], 32); const float dot = (acc[t][0] + lo * (1.f / 32.f)) * s_u[t];
;         if (kq == 0) pl[t * 16 + n16] = (u32x2_t){(unsigned)e[t], __float_as_uint(g[t] * gelu_f(dot) * s_v[t])}; }
;     }
;     if (PART == 1) return;
;     float o[16];
; #pragma unroll
;     for (int i = 0; i < 16; ++i) o[i] = 0.f;
;     for (int j0 = 0; j0 < NTL * 16; j0 += 16) {
;         u32x4_t w[16]; float cj[16];
; #pragma unroll
;         for (int jj = 0; jj < 16; ++jj) { const u32x2_t pr = pl[j0 + jj]; const int ej = __builtin_amdgcn_readfirstlane((int)pr.x); cj[jj] = __uint_as_float(pr.y);
;             w[jj] = *(const u32x4_t*)(v8 + (size_t)ej * D + 16 * lane); }
	v_mul_f32_e32 v85, v85, v136
	v_mul_f32_e32 v6, 0x3d372713, v85
	v_mul_f32_e32 v6, v85, v6
	v_fma_f32 v6, v85, v6, v85
	v_mul_f32_e32 v6, 0x3f4c422a, v6
	v_mul_f32_e32 v6, -2.0, v6
	v_mul_f32_e32 v6, 0x3fb8aa3b, v6
	v_exp_f32_e32 v6, v6
	s_nop 0
	v_add_f32_e32 v6, 1.0, v6
	v_rcp_f32_e32 v6, v6
	s_nop 0
	v_mul_f32_e32 v85, v85, v6
	v_mul_f32_e32 v85, v38, v85
	v_mul_f32_e32 v85, v138, v85
	v_mul_f32_e32 v87, v87, v137
	v_mul_f32_e32 v7, 0x3d372713, v87
	v_mul_f32_e32 v7, v87, v7
	v_fma_f32 v7, v87, v7, v87
	v_mul_f32_e32 v7, 0x3f4c422a, v7
	v_mul_f32_e32 v7, -2.0, v7
	v_mul_f32_e32 v7, 0x3fb8aa3b, v7
	v_exp_f32_e32 v7, v7
	s_nop 0
	v_add_f32_e32 v7, 1.0, v7
	v_rcp_f32_e32 v7, v7
	s_nop 0
	v_mul_f32_e32 v87, v87, v7
	v_mul_f32_e32 v87, v39, v87
	v_mul_f32_e32 v87, v139, v87
	v_mov_b32_e32 v84, v36
	v_mov_b32_e32 v86, v37
	ds_write_b128 v3, v[84:87] offset:4096
	s_waitcnt vmcnt(8)
	v_mul_f32_e32 v89, v89, v140
	v_mul_f32_e32 v6, 0x3d372713, v89
	v_mul_f32_e32 v6, v89, v6
	v_fma_f32 v6, v89, v6, v89
	v_mul_f32_e32 v6, 0x3f4c422a, v6
	v_mul_f32_e32 v6, -2.0, v6
	v_mul_f32_e32 v6, 0x3fb8aa3b, v6
	v_exp_f32_e32 v6, v6
	s_nop 0
	v_add_f32_e32 v6, 1.0, v6
	v_rcp_f32_e32 v6, v6
	s_nop 0
	v_mul_f32_e32 v89, v89, v6
	v_mul_f32_e32 v89, v42, v89
	v_mul_f32_e32 v89, v142, v89
	v_mul_f32_e32 v91, v91, v141
	v_mul_f32_e32 v7, 0x3d372713, v91
	v_mul_f32_e32 v7, v91, v7
	v_fma_f32 v7, v91, v7, v91
	v_mul_f32_e32 v7, 0x3f4c422a, v7
	v_mul_f32_e32 v7, -2.0, v7
	v_mul_f32_e32 v7, 0x3fb8aa3b, v7
	v_exp_f32_e32 v7, v7
	s_nop 0
	v_add_f32_e32 v7, 1.0, v7
	v_rcp_f32_e32 v7, v7
	s_nop 0
	v_mul_f32_e32 v91, v91, v7
	v_mul_f32_e32 v91, v43, v91
	v_mul_f32_e32 v91, v143, v91
	v_mov_b32_e32 v88, v40
	v_mov_b32_e32 v90, v41
	ds_write_b128 v3, v[88:91] offset:5120
	s_waitcnt vmcnt(4)
	v_mul_f32_e32 v93, v93, v144
	v_mul_f32_e32 v6, 0x3d372713, v93
	v_mul_f32_e32 v6, v93, v6
	v_fma_f32 v6, v93, v6, v93
	v_mul_f32_e32 v6, 0x3f4c422a, v6
	v_mul_f32_e32 v6, -2.0, v6
	v_mul_f32_e32 v6, 0x3fb8aa3b, v6
	v_exp_f32_e32 v6, v6
	s_nop 0
	v_add_f32_e32 v6, 1.0, v6
	v_rcp_f32_e32 v6, v6
	s_nop 0
	v_mul_f32_e32 v93, v93, v6
	v_mul_f32_e32 v93, v46, v93
	v_mul_f32_e32 v93, v146, v93
	v_mul_f32_e32 v95, v95, v145
	v_mul_f32_e32 v7, 0x3d372713, v95
	v_mul_f32_e32 v7, v95, v7
	v_fma_f32 v7, v95, v7, v95
	v_mul_f32_e32 v7, 0x3f4c422a, v7
	v_mul_f32_e32 v7, -2.0, v7
	v_mul_f32_e32 v7, 0x3fb8aa3b, v7
	v_exp_f32_e32 v7, v7
	s_nop 0
	v_add_f32_e32 v7, 1.0, v7
	v_rcp_f32_e32 v7, v7
	s_nop 0
	v_mul_f32_e32 v95, v95, v7
	v_mul_f32_e32 v95, v47, v95
	v_mul_f32_e32 v95, v147, v95
	v_mov_b32_e32 v92, v44
	v_mov_b32_e32 v94, v45
	ds_write_b128 v3, v[92:95] offset:6144
	s_waitcnt vmcnt(0)
	v_mul_f32_e32 v97, v97, v148
	v_mul_f32_e32 v6, 0x3d372713, v97
	v_mul_f32_e32 v6, v97, v6
	v_fma_f32 v6, v97, v6, v97
	v_mul_f32_e32 v6, 0x3f4c422a, v6
	v_mul_f32_e32 v6, -2.0, v6
	v_mul_f32_e32 v6, 0x3fb8aa3b, v6
	v_exp_f32_e32 v6, v6
	s_nop 0
	v_add_f32_e32 v6, 1.0, v6
	v_rcp_f32_e32 v6, v6
	s_nop 0
	v_mul_f32_e32 v97, v97, v6
	v_mul_f32_e32 v97, v50, v97
	v_mul_f32_e32 v97, v150, v97
	v_mul_f32_e32 v99, v99, v149
	v_mul_f32_e32 v7, 0x3d372713, v99
	v_mul_f32_e32 v7, v99, v7
	v_fma_f32 v7, v99, v7, v99
	v_mul_f32_e32 v7, 0x3f4c422a, v7
	v_mul_f32_e32 v7, -2.0, v7
	v_mul_f32_e32 v7, 0x3fb8aa3b, v7
	v_exp_f32_e32 v7, v7
	s_nop 0
	v_add_f32_e32 v7, 1.0, v7
	v_rcp_f32_e32 v7, v7
	s_nop 0
	v_mul_f32_e32 v99, v99, v7
	v_mul_f32_e32 v99, v51, v99
	v_mul_f32_e32 v99, v151, v99
	v_mov_b32_e32 v96, v48
	v_mov_b32_e32 v98, v49
	ds_write_b128 v3, v[96:99] offset:7168
	s_waitcnt lgkmcnt(0)
	v_cmp_gt_u32_e32 vcc, 8, v116
	s_nop 1
	s_lshl_b32 s20, s34, 12
	s_lshl_b32 s11, s8, 24
	s_add_u32 s56, s6, 0x27a42100
	s_addc_u32 s57, s7, 0
	s_add_u32 s56, s56, s11
	s_addc_u32 s57, s57, 0
	s_mov_b32 s12, s56
	s_mov_b32 s13, s57
	s_lshl_b32 s11, s48, 12
	s_add_u32 s58, s4, s11
	s_addc_u32 s59, s5, 0
	s_mul_i32 s11, s8, 0x6c000
	s_add_u32 s60, s6, 0x9000
	s_addc_u32 s61, s7, 0
	s_add_u32 s60, s60, s11
	s_addc_u32 s61, s61, 0
	s_mov_b32 s24, 0xff00ff00
	s_mov_b32 s25, 0xff00ff00
	v_and_b32_e32 v2, 7, v1
	v_lshrrev_b32_e32 v3, 3, v1
	v_lshlrev_b32_e32 v4, 4, v2
	v_lshlrev_b32_e32 v5, 7, v3
	v_add_u32_e32 v5, s85, v5
	v_lshlrev_b32_e32 v6, 6, v2
	v_lshl_add_u32 v6, v3, 3, v6
	ds_read_b128 v[26:29], v5 offset:0
	ds_read_b128 v[30:33], v5 offset:16
	ds_read_b128 v[34:37], v5 offset:32
	ds_read_b128 v[38:41], v5 offset:48
	ds_read_b128 v[42:45], v5 offset:64
	ds_read_b128 v[46:49], v5 offset:80
	ds_read_b128 v[50:53], v5 offset:96
	ds_read_b128 v[54:57], v5 offset:112
	s_waitcnt lgkmcnt(0)
	v_lshl_add_u32 v68, v26, 10, v4
	v_lshl_add_u32 v69, v28, 10, v4
	v_lshl_add_u32 v70, v30, 10, v4
	v_lshl_add_u32 v71, v32, 10, v4
	v_lshl_add_u32 v72, v34, 10, v4
	v_lshl_add_u32 v73, v36, 10, v4
	v_lshl_add_u32 v74, v38, 10, v4
	v_lshl_add_u32 v75, v40, 10, v4
	v_lshl_add_u32 v76, v42, 10, v4
	v_lshl_add_u32 v77, v44, 10, v4
	v_lshl_add_u32 v78, v46, 10, v4
	v_lshl_add_u32 v79, v48, 10, v4
	v_lshl_add_u32 v80, v50, 10, v4
	v_lshl_add_u32 v81, v52, 10, v4
	v_lshl_add_u32 v82, v54, 10, v4
	v_lshl_add_u32 v83, v56, 10, v4
	global_load_dwordx4 v[120:123], v68, s[12:13]
	global_load_dwordx4 v[124:127], v69, s[12:13]
	global_load_dwordx4 v[128:131], v70, s[12:13]
	global_load_dwordx4 v[132:135], v71, s[12:13]
	global_load_dwordx4 v[136:139], v72, s[12:13]
	global_load_dwordx4 v[140:143], v73, s[12:13]
	global_load_dwordx4 v[144:147], v74, s[12:13]
	global_load_dwordx4 v[148:151], v75, s[12:13]
	global_load_dwordx4 v[152:155], v76, s[12:13]
	global_load_dwordx4 v[156:159], v77, s[12:13]
	global_load_dwordx4 v[160:163], v78, s[12:13]
	global_load_dwordx4 v[164:167], v79, s[12:13]
	global_load_dwordx4 v[168:171], v80, s[12:13]
	global_load_dwordx4 v[172:175], v81, s[12:13]
	global_load_dwordx4 v[188:191], v82, s[12:13]
	global_load_dwordx4 v[192:195], v83, s[12:13]
	s_mov_b32 s22, 0

; #define LAS __attribute__((address_space(3)))
;     ...
;     for (int j0 = 0; j0 < NTL * 16; j0 += 16) {
;         u32x4_t w[16]; float cj[16];
; #pragma unroll
;         for (int jj = 0; jj < 16; ++jj) { const u32x2_t pr = pl[j0 + jj]; const int ej = __builtin_amdgcn_readfirstlane((int)pr.x); cj[jj] = __uint_as_float(pr.y);
;             w[jj] = *(const u32x4_t*)(v8 + (size_t)ej * D + 16 * lane); }
; #pragma unroll
;         for (int jj = 0; jj < 16; ++jj) { const float c = cj[jj];
; #pragma unroll
;             for (int q = 0; q < 4; ++q) { const f32x2_t lo = __builtin_amdgcn_cvt_pk_f32_fp8((int)w[jj][q], false), hi = __builtin_amdgcn_cvt_pk_f32_fp8((int)w[jj][q], true);
;                 o[4 * q] += c * lo[0]; o[4 * q + 1] += c * lo[1]; o[4 * q + 2] += c * hi[0]; o[4 * q + 3] += c * hi[1]; } }
;     }
;     if (NTL < 8) {
;         if (half == 1) {
; #pragma unroll
;             for (int q = 0; q < 4; ++q) *(LAS f32x4_t*)(xch + lane * 16 + 4 * q) = (f32x4_t){o[4 * q], o[4 * q + 1], o[4 * q + 2], o[4 * q + 3]};
;         }
;         __syncthreads();
;         if (half == 1) return;
; #pragma unroll
;         for (int q = 0; q < 4; ++q) { const f32x4_t t4 = *(const LAS f32x4_t*)(xch + lane * 16 + 4 * q); o[4 * q] += t4[0]; o[4 * q + 1] += t4[1]; o[4 * q + 2] += t4[2]; o[4 * q + 3] += t4[3]; }
;     }
;     const float* gp = gate2 + (size_t)row_seq(r) * 6144 + 16 * lane;
;     float* xp = x + (size_t)r * D + 16 * lane;
; #pragma unroll
;     for (int q = 0; q < 4; ++q) {
;         float4 xa = *(const float4*)(xp + 4 * q); const float4 ga = *(const float4*)(gp + 4 * q);
;         xa.x += ga.x * o[4 * q]; xa.y += ga.y * o[4 * q + 1]; xa.z += ga.z * o[4 * q + 2]; xa.w += ga.w * o[4 * q + 3];
;         *(float4*)(xp + 4 * q) = xa;
.Lg2_nobar:
	s_and_b32 s9, s22, 7
	s_lshr_b32 s10, s22, 3
	s_mul_i32 s11, s9, s20
	s_lshl_b32 s23, s10, 9
	s_add_u32 s14, s58, s11
	s_addc_u32 s15, s59, 0
	s_add_u32 s14, s14, s23
	s_addc_u32 s15, s15, 0
	s_mul_i32 s11, s9, s34
	s_add_u32 s11, s11, s48
	s_lshr_b32 s11, s11, 13
	s_mul_i32 s11, s11, 0x6000
	s_add_u32 s16, s60, s11
	s_addc_u32 s17, s61, 0
	s_add_u32 s16, s16, s23
	s_addc_u32 s17, s17, 0
	global_load_dwordx2 v[58:59], v6, s[14:15] nt
	global_load_dwordx2 v[60:61], v6, s[16:17]
	s_lshl_b32 s9, s9, 10
	v_add_u32_e32 v7, s9, v5
	s_add_u32 s10, s22, 1
	s_and_b32 s9, s10, 7
	s_lshl_b32 s9, s9, 10
	v_add_u32_e32 v8, s9, v5
	s_lshr_b32 s10, s10, 3
	s_lshl_b32 s10, s10, 7
	s_add_u32 s12, s56, s10
	s_addc_u32 s13, s57, 0
	ds_read_b128 v[84:87], v7 offset:0
	ds_read_b128 v[88:91], v7 offset:16
	ds_read_b128 v[92:95], v7 offset:32
	ds_read_b128 v[96:99], v7 offset:48
	ds_read_b128 v[104:107], v7 offset:64
	ds_read_b128 v[108:111], v7 offset:80
	ds_read_b128 v[112:115], v7 offset:96
	ds_read_b128 v[180:183], v7 offset:112
	ds_read_b128 v[26:29], v8 offset:0
	ds_read_b128 v[30:33], v8 offset:16
	ds_read_b128 v[34:37], v8 offset:32
	ds_read_b128 v[38:41], v8 offset:48
	ds_read_b128 v[42:45], v8 offset:64
	ds_read_b128 v[46:49], v8 offset:80
	ds_read_b128 v[50:53], v8 offset:96
	ds_read_b128 v[54:57], v8 offset:112
	s_waitcnt lgkmcnt(0)
	v_lshl_add_u32 v68, v26, 10, v4
	v_lshl_add_u32 v69, v28, 10, v4
	v_lshl_add_u32 v70, v30, 10, v4
	v_lshl_add_u32 v71, v32, 10, v4
	v_lshl_add_u32 v72, v34, 10, v4
	v_lshl_add_u32 v73, v36, 10, v4
	v_lshl_add_u32 v74, v38, 10, v4
	v_lshl_add_u32 v75, v40, 10, v4
	v_lshl_add_u32 v76, v42, 10, v4
	v_lshl_add_u32 v77, v44, 10, v4
	v_lshl_add_u32 v78, v46, 10, v4
	v_lshl_add_u32 v79, v48, 10, v4
	v_lshl_add_u32 v80, v50, 10, v4
	v_lshl_add_u32 v81, v52, 10, v4
	v_lshl_add_u32 v82, v54, 10, v4
	v_lshl_add_u32 v83, v56, 10, v4
	s_waitcnt vmcnt(16)
	v_cvt_pk_f32_fp8_e32 v[26:27], v120
	v_cvt_pk_f32_fp8_sdwa v[28:29], v120 src0_sel:WORD_1
	v_cvt_pk_f32_fp8_e32 v[30:31], v121
	v_cvt_pk_f32_fp8_sdwa v[32:33], v121 src0_sel:WORD_1
	v_cvt_pk_f32_fp8_e32 v[34:35], v122
	v_cvt_pk_f32_fp8_sdwa v[36:37], v122 src0_sel:WORD_1
	v_cvt_pk_f32_fp8_e32 v[38:39], v123
	v_cvt_pk_f32_fp8_sdwa v[40:41], v123 src0_sel:WORD_1
	v_cvt_pk_f32_fp8_e32 v[42:43], v124
	v_cvt_pk_f32_fp8_sdwa v[44:45], v124 src0_sel:WORD_1
	v_cvt_pk_f32_fp8_e32 v[46:47], v125
	v_cvt_pk_f32_fp8_sdwa v[48:49], v125 src0_sel:WORD_1
	v_cvt_pk_f32_fp8_e32 v[50:51], v126
	v_cvt_pk_f32_fp8_sdwa v[52:53], v126 src0_sel:WORD_1
	v_cvt_pk_f32_fp8_e32 v[54:55], v127
	v_cvt_pk_f32_fp8_sdwa v[56:57], v127 src0_sel:WORD_1
	global_load_dwordx4 v[120:123], v68, s[12:13]
	global_load_dwordx4 v[124:127], v69, s[12:13]
	v_pk_mul_f32 v[10:11], v[84:85], v[26:27] op_sel:[1,0]
	v_pk_mul_f32 v[12:13], v[84:85], v[28:29] op_sel:[1,0]
	v_pk_mul_f32 v[14:15], v[84:85], v[30:31] op_sel:[1,0]
	v_pk_mul_f32 v[16:17], v[84:85], v[32:33] op_sel:[1,0]
	v_pk_mul_f32 v[18:19], v[84:85], v[34:35] op_sel:[1,0]
	v_pk_mul_f32 v[20:21], v[84:85], v[36:37] op_sel:[1,0]
	v_pk_mul_f32 v[22:23], v[84:85], v[38:39] op_sel:[1,0]
	v_pk_mul_f32 v[24:25], v[84:85], v[40:41] op_sel:[1,0]
	v_pk_fma_f32 v[10:11], v[86:87], v[42:43], v[10:11] op_sel:[1,0,0]
	v_pk_fma_f32 v[12:13], v[86:87], v[44:45], v[12:13] op_sel:[1,0,0]
	v_pk_fma_f32 v[14:15], v[86:87], v[46:47], v[14:15] op_sel:[1,0,0]
	v_pk_fma_f32 v[16:17], v[86:87], v[48:49], v[16:17] op_sel:[1,0,0]
	v_pk_fma_f32 v[18:19], v[86:87], v[50:51], v[18:19] op_sel:[1,0,0]
	v_pk_fma_f32 v[20:21], v[86:87], v[52:53], v[20:21] op_sel:[1,0,0]
	v_pk_fma_f32 v[22:23], v[86:87], v[54:55], v[22:23] op_sel:[1,0,0]
	v_pk_fma_f32 v[24:25], v[86:87], v[56:57], v[24:25] op_sel:[1,0,0]
	s_waitcnt vmcnt(16)
	v_cvt_pk_f32_fp8_e32 v[26:27], v128
	v_cvt_pk_f32_fp8_sdwa v[28:29], v128 src0_sel:WORD_1
	v_cvt_pk_f32_fp8_e32 v[30:31], v129
	v_cvt_pk_f32_fp8_sdwa v[32:33], v129 src0_sel:WORD_1
	v_cvt_pk_f32_fp8_e32 v[34:35], v130
	v_cvt_pk_f32_fp8_sdwa v[36:37], v130 src0_sel:WORD_1
	v_cvt_pk_f32_fp8_e32 v[38:39], v131
	v_cvt_pk_f32_fp8_sdwa v[40:41], v131 src0_sel:WORD_1
	v_cvt_pk_f32_fp8_e32 v[42:43], v132
	v_cvt_pk_f32_fp8_sdwa v[44:45], v132 src0_sel:WORD_1
	v_cvt_pk_f32_fp8_e32 v[46:47], v133
	v_cvt_pk_f32_fp8_sdwa v[48:49], v133 src0_sel:WORD_1
	v_cvt_pk_f32_fp8_e32 v[50:51], v134
	v_cvt_pk_f32_fp8_sdwa v[52:53], v134 src0_sel:WORD_1
	v_cvt_pk_f32_fp8_e32 v[54:55], v135
	v_cvt_pk_f32_fp8_sdwa v[56:57], v135 src0_sel:WORD_1
	global_load_dwordx4 v[128:131], v70, s[12:13]
	global_load_dwordx4 v[132:135], v71, s[12:13]
	v_pk_fma_f32 v[10:11], v[88:89], v[26:27], v[10:11] op_sel:[1,0,0]
	v_pk_fma_f32 v[12:13], v[88:89], v[28:29], v[12:13] op_sel:[1,0,0]
	v_pk_fma_f32 v[14:15], v[88:89], v[30:31], v[14:15] op_sel:[1,0,0]
	v_pk_fma_f32 v[16:17], v[88:89], v[32:33], v[16:17] op_sel:[1,0,0]
	v_pk_fma_f32 v[18:19], v[88:89], v[34:35], v[18:19] op_sel:[1,0,0]
	v_pk_fma_f32 v[20:21], v[88:89], v[36:37], v[20:21] op_sel:[1,0,0]
	v_pk_fma_f32 v[22:23], v[88:89], v[38:39], v[22:23] op_sel:[1,0,0]
	v_pk_fma_f32 v[24:25], v[88:89], v[40:41], v[24:25] op_sel:[1,0,0]
	v_pk_fma_f32 v[10:11], v[90:91], v[42:43], v[10:11] op_sel:[1,0,0]
	v_pk_fma_f32 v[12:13], v[90:91], v[44:45], v[12:13] op_sel:[1,0,0]
	v_pk_fma_f32 v[14:15], v[90:91], v[46:47], v[14:15] op_sel:[1,0,0]
	v_pk_fma_f32 v[16:17], v[90:91], v[48:49], v[16:17] op_sel:[1,0,0]
	v_pk_fma_f32 v[18:19], v[90:91], v[50:51], v[18:19] op_sel:[1,0,0]
	v_pk_fma_f32 v[20:21], v[90:91], v[52:53], v[20:21] op_sel:[1,0,0]
	v_pk_fma_f32 v[22:23], v[90:91], v[54:55], v[22:23] op_sel:[1,0,0]
	v_pk_fma_f32 v[24:25], v[90:91], v[56:57], v[24:25] op_sel:[1,0,0]
	s_waitcnt vmcnt(16)
;     ...
;         for (int jj = 0; jj < 16; ++jj) { const float c = cj[jj];
; #pragma unroll
;             for (int q = 0; q < 4; ++q) { const f32x2_t lo = __builtin_amdgcn_cvt_pk_f32_fp8((int)w[jj][q], false), hi = __builtin_amdgcn_cvt_pk_f32_fp8((int)w[jj][q], true);
;                 o[4 * q] += c * lo[0]; o[4 * q + 1] += c * lo[1]; o[4 * q + 2] += c * hi[0]; o[4 * q + 3] += c * hi[1]; } }
	v_cvt_pk_f32_fp8_e32 v[26:27], v136
	v_cvt_pk_f32_fp8_sdwa v[28:29], v136 src0_sel:WORD_1
	v_cvt_pk_f32_fp8_e32 v[30:31], v137
	v_cvt_pk_f32_fp8_sdwa v[32:33], v137 src0_sel:WORD_1
	v_cvt_pk_f32_fp8_e32 v[34:35], v138
	v_cvt_pk_f32_fp8_sdwa v[36:37], v138 src0_sel:WORD_1
	v_cvt_pk_f32_fp8_e32 v[38:39], v139
	v_cvt_pk_f32_fp8_sdwa v[40:41], v139 src0_sel:WORD_1
	v_cvt_pk_f32_fp8_e32 v[42:43], v140
	v_cvt_pk_f32_fp8_sdwa v[44:45], v140 src0_sel:WORD_1
	v_cvt_pk_f32_fp8_e32 v[46:47], v141
	v_cvt_pk_f32_fp8_sdwa v[48:49], v141 src0_sel:WORD_1
	v_cvt_pk_f32_fp8_e32 v[50:51], v142
	v_cvt_pk_f32_fp8_sdwa v[52:53], v142 src0_sel:WORD_1
	v_cvt_pk_f32_fp8_e32 v[54:55], v143
	v_cvt_pk_f32_fp8_sdwa v[56:57], v143 src0_sel:WORD_1
	global_load_dwordx4 v[136:139], v72, s[12:13]
	global_load_dwordx4 v[140:143], v73, s[12:13]
	v_pk_fma_f32 v[10:11], v[92:93], v[26:27], v[10:11] op_sel:[1,0,0]
	v_pk_fma_f32 v[12:13], v[92:93], v[28:29], v[12:13] op_sel:[1,0,0]
	v_pk_fma_f32 v[14:15], v[92:93], v[30:31], v[14:15] op_sel:[1,0,0]
	v_pk_fma_f32 v[16:17], v[92:93], v[32:33], v[16:17] op_sel:[1,0,0]
	v_pk_fma_f32 v[18:19], v[92:93], v[34:35], v[18:19] op_sel:[1,0,0]
	v_pk_fma_f32 v[20:21], v[92:93], v[36:37], v[20:21] op_sel:[1,0,0]
	v_pk_fma_f32 v[22:23], v[92:93], v[38:39], v[22:23] op_sel:[1,0,0]
	v_pk_fma_f32 v[24:25], v[92:93], v[40:41], v[24:25] op_sel:[1,0,0]
	v_pk_fma_f32 v[10:11], v[94:95], v[42:43], v[10:11] op_sel:[1,0,0]
	v_pk_fma_f32 v[12:13], v[94:95], v[44:45], v[12:13] op_sel:[1,0,0]
	v_pk_fma_f32 v[14:15], v[94:95], v[46:47], v[14:15] op_sel:[1,0,0]
	v_pk_fma_f32 v[16:17], v[94:95], v[48:49], v[16:17] op_sel:[1,0,0]
	v_pk_fma_f32 v[18:19], v[94:95], v[50:51], v[18:19] op_sel:[1,0,0]
	v_pk_fma_f32 v[20:21], v[94:95], v[52:53], v[20:21] op_sel:[1,0,0]
	v_pk_fma_f32 v[22:23], v[94:95], v[54:55], v[22:23] op_sel:[1,0,0]
	v_pk_fma_f32 v[24:25], v[94:95], v[56:57], v[24:25] op_sel:[1,0,0]
	s_waitcnt vmcnt(16)
	v_cvt_pk_f32_fp8_e32 v[26:27], v144
	v_cvt_pk_f32_fp8_sdwa v[28:29], v144 src0_sel:WORD_1
	v_cvt_pk_f32_fp8_e32 v[30:31], v145
	v_cvt_pk_f32_fp8_sdwa v[32:33], v145 src0_sel:WORD_1
	v_cvt_pk_f32_fp8_e32 v[34:35], v146
	v_cvt_pk_f32_fp8_sdwa v[36:37], v146 src0_sel:WORD_1
	v_cvt_pk_f32_fp8_e32 v[38:39], v147
	v_cvt_pk_f32_fp8_sdwa v[40:41], v147 src0_sel:WORD_1
	v_cvt_pk_f32_fp8_e32 v[42:43], v148
	v_cvt_pk_f32_fp8_sdwa v[44:45], v148 src0_sel:WORD_1
	v_cvt_pk_f32_fp8_e32 v[46:47], v149
	v_cvt_pk_f32_fp8_sdwa v[48:49], v149 src0_sel:WORD_1
	v_cvt_pk_f32_fp8_e32 v[50:51], v150
	v_cvt_pk_f32_fp8_sdwa v[52:53], v150 src0_sel:WORD_1
	v_cvt_pk_f32_fp8_e32 v[54:55], v151
	v_cvt_pk_f32_fp8_sdwa v[56:57], v151 src0_sel:WORD_1
	global_load_dwordx4 v[144:147], v74, s[12:13]
	global_load_dwordx4 v[148:151], v75, s[12:13]
	v_pk_fma_f32 v[10:11], v[96:97], v[26:27], v[10:11] op_sel:[1,0,0]
	v_pk_fma_f32 v[12:13], v[96:97], v[28:29], v[12:13] op_sel:[1,0,0]
	v_pk_fma_f32 v[14:15], v[96:97], v[30:31], v[14:15] op_sel:[1,0,0]
	v_pk_fma_f32 v[16:17], v[96:97], v[32:33], v[16:17] op_sel:[1,0,0]
	v_pk_fma_f32 v[18:19], v[96:97], v[34:35], v[18:19] op_sel:[1,0,0]
	v_pk_fma_f32 v[20:21], v[96:97], v[36:37], v[20:21] op_sel:[1,0,0]
	v_pk_fma_f32 v[22:23], v[96:97], v[38:39], v[22:23] op_sel:[1,0,0]
	v_pk_fma_f32 v[24:25], v[96:97], v[40:41], v[24:25] op_sel:[1,0,0]
	v_pk_fma_f32 v[10:11], v[98:99], v[42:43], v[10:11] op_sel:[1,0,0]
	v_pk_fma_f32 v[12:13], v[98:99], v[44:45], v[12:13] op_sel:[1,0,0]
	v_pk_fma_f32 v[14:15], v[98:99], v[46:47], v[14:15] op_sel:[1,0,0]
	v_pk_fma_f32 v[16:17], v[98:99], v[48:49], v[16:17] op_sel:[1,0,0]
	v_pk_fma_f32 v[18:19], v[98:99], v[50:51], v[18:19] op_sel:[1,0,0]
	v_pk_fma_f32 v[20:21], v[98:99], v[52:53], v[20:21] op_sel:[1,0,0]
	v_pk_fma_f32 v[22:23], v[98:99], v[54:55], v[22:23] op_sel:[1,0,0]
	v_pk_fma_f32 v[24:25], v[98:99], v[56:57], v[24:25] op_sel:[1,0,0]
	s_waitcnt vmcnt(16)
	v_cvt_pk_f32_fp8_e32 v[26:27], v152
	v_cvt_pk_f32_fp8_sdwa v[28:29], v152 src0_sel:WORD_1
	v_cvt_pk_f32_fp8_e32 v[30:31], v153
	v_cvt_pk_f32_fp8_sdwa v[32:33], v153 src0_sel:WORD_1
	v_cvt_pk_f32_fp8_e32 v[34:35], v154
	v_cvt_pk_f32_fp8_sdwa v[36:37], v154 src0_sel:WORD_1
	v_cvt_pk_f32_fp8_e32 v[38:39], v155
	v_cvt_pk_f32_fp8_sdwa v[40:41], v155 src0_sel:WORD_1
	v_cvt_pk_f32_fp8_e32 v[42:43], v156
	v_cvt_pk_f32_fp8_sdwa v[44:45], v156 src0_sel:WORD_1
	v_cvt_pk_f32_fp8_e32 v[46:47], v157
	v_cvt_pk_f32_fp8_sdwa v[48:49], v157 src0_sel:WORD_1
	v_cvt_pk_f32_fp8_e32 v[50:51], v158
	v_cvt_pk_f32_fp8_sdwa v[52:53], v158 src0_sel:WORD_1
	v_cvt_pk_f32_fp8_e32 v[54:55], v159
	v_cvt_pk_f32_fp8_sdwa v[56:57], v159 src0_sel:WORD_1
	global_load_dwordx4 v[152:155], v76, s[12:13]
	global_load_dwordx4 v[156:159], v77, s[12:13]
	v_pk_fma_f32 v[10:11], v[104:105], v[26:27], v[10:11] op_sel:[1,0,0]
	v_pk_fma_f32 v[12:13], v[104:105], v[28:29], v[12:13] op_sel:[1,0,0]
	v_pk_fma_f32 v[14:15], v[104:105], v[30:31], v[14:15] op_sel:[1,0,0]
	v_pk_fma_f32 v[16:17], v[104:105], v[32:33], v[16:17] op_sel:[1,0,0]
	v_pk_fma_f32 v[18:19], v[104:105], v[34:35], v[18:19] op_sel:[1,0,0]
	v_pk_fma_f32 v[20:21], v[104:105], v[36:37], v[20:21] op_sel:[1,0,0]
	v_pk_fma_f32 v[22:23], v[104:105], v[38:39], v[22:23] op_sel:[1,0,0]
	v_pk_fma_f32 v[24:25], v[104:105], v[40:41], v[24:25] op_sel:[1,0,0]
	v_pk_fma_f32 v[10:11], v[106:107], v[42:43], v[10:11] op_sel:[1,0,0]
	v_pk_fma_f32 v[12:13], v[106:107], v[44:45], v[12:13] op_sel:[1,0,0]
	v_pk_fma_f32 v[14:15], v[106:107], v[46:47], v[14:15] op_sel:[1,0,0]
	v_pk_fma_f32 v[16:17], v[106:107], v[48:49], v[16:17] op_sel:[1,0,0]
	v_pk_fma_f32 v[18:19], v[106:107], v[50:51], v[18:19] op_sel:[1,0,0]
	v_pk_fma_f32 v[20:21], v[106:107], v[52:53], v[20:21] op_sel:[1,0,0]
	v_pk_fma_f32 v[22:23], v[106:107], v[54:55], v[22:23] op_sel:[1,0,0]
	v_pk_fma_f32 v[24:25], v[106:107], v[56:57], v[24:25] op_sel:[1,0,0]
	s_waitcnt vmcnt(16)
;     ...
;         for (int jj = 0; jj < 16; ++jj) { const float c = cj[jj];
; #pragma unroll
;             for (int q = 0; q < 4; ++q) { const f32x2_t lo = __builtin_amdgcn_cvt_pk_f32_fp8((int)w[jj][q], false), hi = __builtin_amdgcn_cvt_pk_f32_fp8((int)w[jj][q], true);
;                 o[4 * q] += c * lo[0]; o[4 * q + 1] += c * lo[1]; o[4 * q + 2] += c * hi[0]; o[4 * q + 3] += c * hi[1]; } }
	v_cvt_pk_f32_fp8_e32 v[26:27], v160
	v_cvt_pk_f32_fp8_sdwa v[28:29], v160 src0_sel:WORD_1
	v_cvt_pk_f32_fp8_e32 v[30:31], v161
	v_cvt_pk_f32_fp8_sdwa v[32:33], v161 src0_sel:WORD_1
	v_cvt_pk_f32_fp8_e32 v[34:35], v162
	v_cvt_pk_f32_fp8_sdwa v[36:37], v162 src0_sel:WORD_1
	v_cvt_pk_f32_fp8_e32 v[38:39], v163
	v_cvt_pk_f32_fp8_sdwa v[40:41], v163 src0_sel:WORD_1
	v_cvt_pk_f32_fp8_e32 v[42:43], v164
	v_cvt_pk_f32_fp8_sdwa v[44:45], v164 src0_sel:WORD_1
	v_cvt_pk_f32_fp8_e32 v[46:47], v165
	v_cvt_pk_f32_fp8_sdwa v[48:49], v165 src0_sel:WORD_1
	v_cvt_pk_f32_fp8_e32 v[50:51], v166
	v_cvt_pk_f32_fp8_sdwa v[52:53], v166 src0_sel:WORD_1
	v_cvt_pk_f32_fp8_e32 v[54:55], v167
	v_cvt_pk_f32_fp8_sdwa v[56:57], v167 src0_sel:WORD_1
	global_load_dwordx4 v[160:163], v78, s[12:13]
	global_load_dwordx4 v[164:167], v79, s[12:13]
	v_pk_fma_f32 v[10:11], v[108:109], v[26:27], v[10:11] op_sel:[1,0,0]
	v_pk_fma_f32 v[12:13], v[108:109], v[28:29], v[12:13] op_sel:[1,0,0]
	v_pk_fma_f32 v[14:15], v[108:109], v[30:31], v[14:15] op_sel:[1,0,0]
	v_pk_fma_f32 v[16:17], v[108:109], v[32:33], v[16:17] op_sel:[1,0,0]
	v_pk_fma_f32 v[18:19], v[108:109], v[34:35], v[18:19] op_sel:[1,0,0]
	v_pk_fma_f32 v[20:21], v[108:109], v[36:37], v[20:21] op_sel:[1,0,0]
	v_pk_fma_f32 v[22:23], v[108:109], v[38:39], v[22:23] op_sel:[1,0,0]
	v_pk_fma_f32 v[24:25], v[108:109], v[40:41], v[24:25] op_sel:[1,0,0]
	v_pk_fma_f32 v[10:11], v[110:111], v[42:43], v[10:11] op_sel:[1,0,0]
	v_pk_fma_f32 v[12:13], v[110:111], v[44:45], v[12:13] op_sel:[1,0,0]
	v_pk_fma_f32 v[14:15], v[110:111], v[46:47], v[14:15] op_sel:[1,0,0]
	v_pk_fma_f32 v[16:17], v[110:111], v[48:49], v[16:17] op_sel:[1,0,0]
	v_pk_fma_f32 v[18:19], v[110:111], v[50:51], v[18:19] op_sel:[1,0,0]
	v_pk_fma_f32 v[20:21], v[110:111], v[52:53], v[20:21] op_sel:[1,0,0]
	v_pk_fma_f32 v[22:23], v[110:111], v[54:55], v[22:23] op_sel:[1,0,0]
	v_pk_fma_f32 v[24:25], v[110:111], v[56:57], v[24:25] op_sel:[1,0,0]
	s_waitcnt vmcnt(16)
	v_cvt_pk_f32_fp8_e32 v[26:27], v168
	v_cvt_pk_f32_fp8_sdwa v[28:29], v168 src0_sel:WORD_1
	v_cvt_pk_f32_fp8_e32 v[30:31], v169
	v_cvt_pk_f32_fp8_sdwa v[32:33], v169 src0_sel:WORD_1
	v_cvt_pk_f32_fp8_e32 v[34:35], v170
	v_cvt_pk_f32_fp8_sdwa v[36:37], v170 src0_sel:WORD_1
	v_cvt_pk_f32_fp8_e32 v[38:39], v171
	v_cvt_pk_f32_fp8_sdwa v[40:41], v171 src0_sel:WORD_1
	v_cvt_pk_f32_fp8_e32 v[42:43], v172
	v_cvt_pk_f32_fp8_sdwa v[44:45], v172 src0_sel:WORD_1
	v_cvt_pk_f32_fp8_e32 v[46:47], v173
	v_cvt_pk_f32_fp8_sdwa v[48:49], v173 src0_sel:WORD_1
	v_cvt_pk_f32_fp8_e32 v[50:51], v174
	v_cvt_pk_f32_fp8_sdwa v[52:53], v174 src0_sel:WORD_1
	v_cvt_pk_f32_fp8_e32 v[54:55], v175
	v_cvt_pk_f32_fp8_sdwa v[56:57], v175 src0_sel:WORD_1
	global_load_dwordx4 v[168:171], v80, s[12:13]
	global_load_dwordx4 v[172:175], v81, s[12:13]
	v_pk_fma_f32 v[10:11], v[112:113], v[26:27], v[10:11] op_sel:[1,0,0]
	v_pk_fma_f32 v[12:13], v[112:113], v[28:29], v[12:13] op_sel:[1,0,0]
	v_pk_fma_f32 v[14:15], v[112:113], v[30:31], v[14:15] op_sel:[1,0,0]
	v_pk_fma_f32 v[16:17], v[112:113], v[32:33], v[16:17] op_sel:[1,0,0]
	v_pk_fma_f32 v[18:19], v[112:113], v[34:35], v[18:19] op_sel:[1,0,0]
	v_pk_fma_f32 v[20:21], v[112:113], v[36:37], v[20:21] op_sel:[1,0,0]
	v_pk_fma_f32 v[22:23], v[112:113], v[38:39], v[22:23] op_sel:[1,0,0]
	v_pk_fma_f32 v[24:25], v[112:113], v[40:41], v[24:25] op_sel:[1,0,0]
	v_pk_fma_f32 v[10:11], v[114:115], v[42:43], v[10:11] op_sel:[1,0,0]
	v_pk_fma_f32 v[12:13], v[114:115], v[44:45], v[12:13] op_sel:[1,0,0]
	v_pk_fma_f32 v[14:15], v[114:115], v[46:47], v[14:15] op_sel:[1,0,0]
	v_pk_fma_f32 v[16:17], v[114:115], v[48:49], v[16:17] op_sel:[1,0,0]
	v_pk_fma_f32 v[18:19], v[114:115], v[50:51], v[18:19] op_sel:[1,0,0]
	v_pk_fma_f32 v[20:21], v[114:115], v[52:53], v[20:21] op_sel:[1,0,0]
	v_pk_fma_f32 v[22:23], v[114:115], v[54:55], v[22:23] op_sel:[1,0,0]
	v_pk_fma_f32 v[24:25], v[114:115], v[56:57], v[24:25] op_sel:[1,0,0]
	s_waitcnt vmcnt(16)
;     DEVI float* wsmall() const { return (float*)(ws + WS_WSMALL); }
; DEVI cfp_t inp(int i) { const __attribute__((address_space(4))) cfp_t* k = (const __attribute__((address_space(4))) cfp_t*)__builtin_amdgcn_kernarg_segment_ptr(); typedef const __attribute__((address_space(1))) float* gcfp_t; const gcfp_t r = *(const volatile __attribute__((address_space(4))) gcfp_t*)(k + i); return (cfp_t)r; }
; #define LAS __attribute__((address_space(3)))
;     ...
;         for (int jj = 0; jj < 16; ++jj) { const float c = cj[jj];
; #pragma unroll
;             for (int q = 0; q < 4; ++q) { const f32x2_t lo = __builtin_amdgcn_cvt_pk_f32_fp8((int)w[jj][q], false), hi = __builtin_amdgcn_cvt_pk_f32_fp8((int)w[jj][q], true);
;                 o[4 * q] += c * lo[0]; o[4 * q + 1] += c * lo[1]; o[4 * q + 2] += c * hi[0]; o[4 * q + 3] += c * hi[1]; } }
;     }
;     if (NTL < 8) {
;         if (half == 1) {
; #pragma unroll
;             for (int q = 0; q < 4; ++q) *(LAS f32x4_t*)(xch + lane * 16 + 4 * q) = (f32x4_t){o[4 * q], o[4 * q + 1], o[4 * q + 2], o[4 * q + 3]};
;         }
;         __syncthreads();
;         if (half == 1) return;
; #pragma unroll
;         for (int q = 0; q < 4; ++q) { const f32x4_t t4 = *(const LAS f32x4_t*)(xch + lane * 16 + 4 * q); o[4 * q] += t4[0]; o[4 * q + 1] += t4[1]; o[4 * q + 2] += t4[2]; o[4 * q + 3] += t4[3]; }
;     }
;     const float* gp = gate2 + (size_t)row_seq(r) * 6144 + 16 * lane;
;     float* xp = x + (size_t)r * D + 16 * lane;
; #pragma unroll
;     for (int q = 0; q < 4; ++q) {
;         float4 xa = *(const float4*)(xp + 4 * q); const float4 ga = *(const float4*)(gp + 4 * q);
;         xa.x += ga.x * o[4 * q]; xa.y += ga.y * o[4 * q + 1]; xa.z += ga.z * o[4 * q + 2]; xa.w += ga.w * o[4 * q + 3];
;         *(float4*)(xp + 4 * q) = xa;
; template <int WHICH> DEVI void adaln_apply(const P& p, int l, int r, int lane_in, float (&v)[16]) {
;     ...
;         const float* dtb = inp(16) + l * 8; const float* fb = inp(22) + l * 4;
;         const float* ws = p.wsmall() + (size_t)l * 12 * D + 16 * lane;
;         float dot[12];
; #pragma unroll
;         for (int jj = 0; jj < 12; ++jj) { float a = 0.f;
; #pragma unroll
;             for (int q = 0; q < 4; ++q) { const float4 w = *(const float4*)(ws + (size_t)jj * D + 4 * q); a += v[4 * q] * w.x + v[4 * q + 1] * w.y + v[4 * q + 2] * w.z + v[4 * q + 3] * w.w; }
	v_cvt_pk_f32_fp8_e32 v[26:27], v188
	v_cvt_pk_f32_fp8_sdwa v[28:29], v188 src0_sel:WORD_1
	v_cvt_pk_f32_fp8_e32 v[30:31], v189
	v_cvt_pk_f32_fp8_sdwa v[32:33], v189 src0_sel:WORD_1
	v_cvt_pk_f32_fp8_e32 v[34:35], v190
	v_cvt_pk_f32_fp8_sdwa v[36:37], v190 src0_sel:WORD_1
	v_cvt_pk_f32_fp8_e32 v[38:39], v191
	v_cvt_pk_f32_fp8_sdwa v[40:41], v191 src0_sel:WORD_1
	v_cvt_pk_f32_fp8_e32 v[42:43], v192
	v_cvt_pk_f32_fp8_sdwa v[44:45], v192 src0_sel:WORD_1
	v_cvt_pk_f32_fp8_e32 v[46:47], v193
	v_cvt_pk_f32_fp8_sdwa v[48:49], v193 src0_sel:WORD_1
	v_cvt_pk_f32_fp8_e32 v[50:51], v194
	v_cvt_pk_f32_fp8_sdwa v[52:53], v194 src0_sel:WORD_1
	v_cvt_pk_f32_fp8_e32 v[54:55], v195
	v_cvt_pk_f32_fp8_sdwa v[56:57], v195 src0_sel:WORD_1
	global_load_dwordx4 v[188:191], v82, s[12:13]
	global_load_dwordx4 v[192:195], v83, s[12:13]
	v_pk_fma_f32 v[10:11], v[180:181], v[26:27], v[10:11] op_sel:[1,0,0]
	v_pk_fma_f32 v[12:13], v[180:181], v[28:29], v[12:13] op_sel:[1,0,0]
	v_pk_fma_f32 v[14:15], v[180:181], v[30:31], v[14:15] op_sel:[1,0,0]
	v_pk_fma_f32 v[16:17], v[180:181], v[32:33], v[16:17] op_sel:[1,0,0]
	v_pk_fma_f32 v[18:19], v[180:181], v[34:35], v[18:19] op_sel:[1,0,0]
	v_pk_fma_f32 v[20:21], v[180:181], v[36:37], v[20:21] op_sel:[1,0,0]
	v_pk_fma_f32 v[22:23], v[180:181], v[38:39], v[22:23] op_sel:[1,0,0]
	v_pk_fma_f32 v[24:25], v[180:181], v[40:41], v[24:25] op_sel:[1,0,0]
	v_pk_fma_f32 v[10:11], v[182:183], v[42:43], v[10:11] op_sel:[1,0,0]
	v_pk_fma_f32 v[12:13], v[182:183], v[44:45], v[12:13] op_sel:[1,0,0]
	v_pk_fma_f32 v[14:15], v[182:183], v[46:47], v[14:15] op_sel:[1,0,0]
	v_pk_fma_f32 v[16:17], v[182:183], v[48:49], v[16:17] op_sel:[1,0,0]
	v_pk_fma_f32 v[18:19], v[182:183], v[50:51], v[18:19] op_sel:[1,0,0]
	v_pk_fma_f32 v[20:21], v[182:183], v[52:53], v[20:21] op_sel:[1,0,0]
	v_pk_fma_f32 v[22:23], v[182:183], v[54:55], v[22:23] op_sel:[1,0,0]
	v_pk_fma_f32 v[24:25], v[182:183], v[56:57], v[24:25] op_sel:[1,0,0]
	s_nop 1
	v_permlane32_swap_b32_e32 v10, v18
	v_permlane32_swap_b32_e32 v11, v19
	v_permlane32_swap_b32_e32 v12, v20
	v_permlane32_swap_b32_e32 v13, v21
	v_permlane32_swap_b32_e32 v14, v22
	v_permlane32_swap_b32_e32 v15, v23
	v_permlane32_swap_b32_e32 v16, v24
	v_permlane32_swap_b32_e32 v17, v25
	v_add_f32_e32 v10, v10, v18
	v_add_f32_e32 v11, v11, v19
	v_add_f32_e32 v12, v12, v20
	v_add_f32_e32 v13, v13, v21
	v_add_f32_e32 v14, v14, v22
	v_add_f32_e32 v15, v15, v23
	v_add_f32_e32 v16, v16, v24
	v_add_f32_e32 v17, v17, v25
	s_nop 1
	v_permlane16_swap_b32_e32 v10, v14
	v_permlane16_swap_b32_e32 v11, v15
	v_permlane16_swap_b32_e32 v12, v16
	v_permlane16_swap_b32_e32 v13, v17
	v_add_f32_e32 v10, v10, v14
	v_add_f32_e32 v11, v11, v15
	v_add_f32_e32 v12, v12, v16
	v_add_f32_e32 v13, v13, v17
	v_cndmask_b32_e64 v14, v10, v12, s[24:25]
	v_cndmask_b32_e64 v16, v12, v10, s[24:25]
	v_cndmask_b32_e64 v15, v11, v13, s[24:25]
	v_cndmask_b32_e64 v17, v13, v11, s[24:25]
	s_nop 1
	v_add_f32_dpp v62, v16, v14 row_ror:8 row_mask:0xf bank_mask:0xf
	v_add_f32_dpp v63, v17, v15 row_ror:8 row_mask:0xf bank_mask:0xf
	s_waitcnt vmcnt(16)
	v_pk_fma_f32 v[58:59], v[62:63], v[60:61], v[58:59]
	global_store_dwordx2 v6, v[58:59], s[14:15] nt
	s_add_u32 s22, s22, 1
	s_cmp_lg_u32 s22, 64
	s_cbranch_scc1 .Lg2_loop
	s_waitcnt vmcnt(0)
	v_cmp_gt_u32_e32 vcc, 8, v116
	s_nop 1
	s_add_u32 s9, s8, 1
	s_mul_i32 s9, s9, 0xc000
	s_add_u32 s10, s6, 0x1f812100
	s_addc_u32 s11, s7, 0
	s_add_u32 s10, s10, s9
	s_addc_u32 s11, s11, 0
	s_lshr_b32 s12, s85, 13
	s_mul_i32 s12, s12, 0x1800
	v_lshlrev_b32_e32 v2, 4, v1
	v_add_u32_e32 v2, s12, v2
	v_add_u32_e32 v4, 0x1000, v2
	global_load_dwordx4 v[132:135], v2, s[10:11] offset:0
	global_load_dwordx4 v[136:139], v2, s[10:11] offset:1024
	global_load_dwordx4 v[140:143], v2, s[10:11] offset:2048
	global_load_dwordx4 v[144:147], v2, s[10:11] offset:3072
	global_load_dwordx4 v[148:151], v4, s[10:11] offset:0
	global_load_dwordx4 v[152:155], v4, s[10:11] offset:1024
	v_add_u32_e32 v3, 0x14100, v2
	s_waitcnt vmcnt(0)
	ds_write_b128 v3, v[132:135] offset:0
	ds_write_b128 v3, v[136:139] offset:1024
	ds_write_b128 v3, v[140:143] offset:2048
	ds_write_b128 v3, v[144:147] offset:3072
	ds_write_b128 v3, v[148:151] offset:4096
	ds_write_b128 v3, v[152:155] offset:5120
	s_waitcnt lgkmcnt(0)
	s_barrier
	s_ashr_i32 s9, s8, 31
	s_lshl_b64 s[18:19], s[8:9], 24
	s_lshl_b64 s[10:11], s[8:9], 16
	s_add_u32 s9, s6, s10
	s_addc_u32 s13, s7, s11
	s_add_u32 s10, s9, 0x2fa42100
	s_addc_u32 s11, s13, 0
	s_add_u32 s12, s9, 0x2fa82100
	s_addc_u32 s13, s13, 0
	s_add_u32 s14, s6, 0x1b292100
	s_addc_u32 s15, s7, 0
	s_add_u32 s16, s6, 0x1bb12100
	s_addc_u32 s17, s7, 0
	s_add_u32 s18, s6, s18
	s_addc_u32 s19, s7, s19
	v_lshl_add_u64 v[2:3], s[18:19], 0, v[102:103]
	s_mov_b64 s[20:21], 0x1fa42100
	v_lshl_add_u64 v[104:105], v[2:3], 0, s[20:21]
	v_mov_b32_e32 v2, 0x1100000
	v_cndmask_b32_e64 v66, v2, 0, vcc
	v_lshl_add_u64 v[2:3], s[6:7], 0, v[66:67]
	s_add_u32 s49, s6, 0x4000
	v_lshl_add_u64 v[2:3], v[2:3], 0, v[102:103]
	s_mov_b64 s[20:21], 0x2fac2100
	s_addc_u32 s50, s7, 0
	v_lshl_add_u64 v[106:107], v[2:3], 0, s[20:21]
	s_add_u32 s20, s49, s47
	v_lshl_add_u64 v[2:3], s[18:19], 0, v[100:101]
	s_mov_b64 s[18:19], 0x27a42100
	s_addc_u32 s21, s50, s46
	v_lshl_add_u64 v[108:109], v[2:3], 0, s[18:19]
	v_lshlrev_b64 v[2:3], 2, v[100:101]
	v_lshl_add_u64 v[4:5], s[20:21], 0, v[2:3]
	s_mov_b64 s[18:19], 0x5000
	s_cmp_lt_i32 s8, 3
	v_lshl_add_u64 v[110:111], v[4:5], 0, s[18:19]
	s_cselect_b64 s[18:19], -1, 0
	s_add_i32 s24, s8, 1
	s_ashr_i32 s25, s24, 31
	s_lshl_b64 s[20:21], s[24:25], 12
	s_add_u32 s55, s6, 0x20e100
	s_addc_u32 s56, s7, 0
	s_lshl_b32 s26, s24, 2
	s_ashr_i32 s27, s26, 31
	s_mul_i32 s23, s24, 0xc000
	s_mul_hi_i32 s22, s24, 0xc000
	s_add_u32 s23, s6, s23
	s_addc_u32 s28, s7, s22
	s_add_u32 s22, s23, 0x1f812100
	s_addc_u32 s23, s28, 0
	s_add_u32 s57, s6, 0xcb8a100
	s_addc_u32 s58, s7, 0
	s_lshl_b64 s[28:29], s[24:25], 18
	s_add_u32 s59, s4, s28
	s_addc_u32 s60, s5, s29
	s_lshl_b32 s28, s24, 3
	s_ashr_i32 s29, s28, 31
	s_add_u32 s61, s6, 0xacda100
	s_mov_b32 s9, 0
	v_lshl_add_u64 v[112:113], s[4:5], 0, v[2:3]
	s_mul_hi_i32 s51, s24, 18
	s_mul_i32 s54, s24, 18
	s_addc_u32 s62, s7, 0
	s_lshl_b64 s[24:25], s[26:27], 2
	s_lshl_b64 s[26:27], s[28:29], 2
	s_mov_b32 s63, s48
	s_branch .LBB0_1087
